# EpiSwiglu epilogue rewritten (same math, packed pairs interleaved), prompt cache-output copy pipelined, EpiResid loads-first with quad-contiguous lane order
# speedup vs baseline: 1.0568x; 1.0224x over previous
; #define LAS __attribute__((address_space(3)))
;     __device__ __forceinline__ void operator()(const f32x4 (&acc)[2][2][4][2], const Unit& u, const LAS float* rsl, int wr, int wc, int fr, int fq) const {
;         const int col0 = u.pn * 128 + wc * 32 + 8 * fq;
; #pragma unroll
;         for (int ai = 0; ai < 2; ++ai)
; #pragma unroll
;             for (int m = 0; m < 4; ++m) {
;                 const int rl = ai * HALF + wr * 64 + m * 16 + fr, row = u.pm * BM + rl;
;                 const float rs = rsl[rl];
;                 float o[8];
; #pragma unroll
;                 for (int n = 0; n < 2; ++n)
; #pragma unroll
;                     for (int e = 0; e < 4; ++e) {
;                         const float g = acc[ai][0][m][n][e] * rs, up = acc[ai][1][m][n][e] * rs;
;                         const float sg = g * __builtin_amdgcn_rcpf(1.0f + __builtin_amdgcn_exp2f(-g * LOG2E));
;                         o[n * 4 + e] = sg * up;
;                     }
;                 *(bf16x8*)(O + (size_t)row * DFF + col0) = pack8(o);
;             }
;     }
.LBB0_383:
	s_add_u32 s34, s4, 0xffffff00
	s_addc_u32 s35, s5, -1
	v_readlane_b32 s36, v254, 63
	v_readlane_b32 s37, v255, 0
	s_lshl_b32 s4, s16, 8
	s_mov_b64 s[54:55], 0x100
	v_lshl_add_u32 v156, s45, 10, v154
	ds_read_b32 v160, v156
	ds_read_b32 v162, v156 offset:64
	ds_read_b32 v164, v156 offset:128
	ds_read_b32 v166, v156 offset:192
	ds_read_b32 v168, v156 offset:512
	ds_read_b32 v170, v156 offset:576
	ds_read_b32 v172, v156 offset:640
	ds_read_b32 v174, v156 offset:704
	v_lshl_or_b32 v142, s14, 7, v153
	v_lshlrev_b32_e32 v142, 1, v142
	v_mov_b32_e32 v176, 0xbfb8aa3b
	v_mov_b32_e32 v178, 1.0
	s_waitcnt lgkmcnt(0)
	v_pk_mul_f32 v[94:95], v[94:95], v[160:161] op_sel_hi:[1,0]
	v_pk_mul_f32 v[96:97], v[96:97], v[160:161] op_sel_hi:[1,0]
	v_pk_mul_f32 v[90:91], v[90:91], v[160:161] op_sel_hi:[1,0]
	v_pk_mul_f32 v[92:93], v[92:93], v[160:161] op_sel_hi:[1,0]
	v_pk_mul_f32 v[86:87], v[86:87], v[162:163] op_sel_hi:[1,0]
	v_pk_mul_f32 v[88:89], v[88:89], v[162:163] op_sel_hi:[1,0]
	v_pk_mul_f32 v[82:83], v[82:83], v[162:163] op_sel_hi:[1,0]
	v_pk_mul_f32 v[84:85], v[84:85], v[162:163] op_sel_hi:[1,0]
	v_pk_mul_f32 v[62:63], v[62:63], v[160:161] op_sel_hi:[1,0]
	v_pk_mul_f32 v[64:65], v[64:65], v[160:161] op_sel_hi:[1,0]
	v_pk_mul_f32 v[58:59], v[58:59], v[160:161] op_sel_hi:[1,0]
	v_pk_mul_f32 v[60:61], v[60:61], v[160:161] op_sel_hi:[1,0]
	v_pk_mul_f32 v[54:55], v[54:55], v[162:163] op_sel_hi:[1,0]
	v_pk_mul_f32 v[56:57], v[56:57], v[162:163] op_sel_hi:[1,0]
	v_pk_mul_f32 v[50:51], v[50:51], v[162:163] op_sel_hi:[1,0]
	v_pk_mul_f32 v[52:53], v[52:53], v[162:163] op_sel_hi:[1,0]
	v_pk_mul_f32 v[180:181], v[94:95], v[176:177] op_sel_hi:[1,0]
	v_pk_mul_f32 v[182:183], v[96:97], v[176:177] op_sel_hi:[1,0]
	v_pk_mul_f32 v[184:185], v[90:91], v[176:177] op_sel_hi:[1,0]
	v_pk_mul_f32 v[186:187], v[92:93], v[176:177] op_sel_hi:[1,0]
	v_pk_mul_f32 v[188:189], v[86:87], v[176:177] op_sel_hi:[1,0]
	v_pk_mul_f32 v[190:191], v[88:89], v[176:177] op_sel_hi:[1,0]
	v_pk_mul_f32 v[192:193], v[82:83], v[176:177] op_sel_hi:[1,0]
	v_pk_mul_f32 v[194:195], v[84:85], v[176:177] op_sel_hi:[1,0]
	v_exp_f32_e32 v180, v180
	v_exp_f32_e32 v181, v181
	v_exp_f32_e32 v182, v182
	v_exp_f32_e32 v183, v183
	v_exp_f32_e32 v184, v184
	v_exp_f32_e32 v185, v185
	v_exp_f32_e32 v186, v186
	v_exp_f32_e32 v187, v187
	v_exp_f32_e32 v188, v188
	v_exp_f32_e32 v189, v189
	v_exp_f32_e32 v190, v190
	v_exp_f32_e32 v191, v191
	v_exp_f32_e32 v192, v192
	v_exp_f32_e32 v193, v193
	v_exp_f32_e32 v194, v194
	v_exp_f32_e32 v195, v195
	v_pk_add_f32 v[180:181], v[180:181], v[178:179] op_sel_hi:[1,0]
	v_pk_add_f32 v[182:183], v[182:183], v[178:179] op_sel_hi:[1,0]
	v_pk_add_f32 v[184:185], v[184:185], v[178:179] op_sel_hi:[1,0]
	v_pk_add_f32 v[186:187], v[186:187], v[178:179] op_sel_hi:[1,0]
	v_pk_add_f32 v[188:189], v[188:189], v[178:179] op_sel_hi:[1,0]
	v_pk_add_f32 v[190:191], v[190:191], v[178:179] op_sel_hi:[1,0]
	v_pk_add_f32 v[192:193], v[192:193], v[178:179] op_sel_hi:[1,0]
	v_pk_add_f32 v[194:195], v[194:195], v[178:179] op_sel_hi:[1,0]
	v_rcp_f32_e32 v180, v180
	v_rcp_f32_e32 v181, v181
	v_rcp_f32_e32 v182, v182
	v_rcp_f32_e32 v183, v183
	v_rcp_f32_e32 v184, v184
	v_rcp_f32_e32 v185, v185
	v_rcp_f32_e32 v186, v186
	v_rcp_f32_e32 v187, v187
	v_rcp_f32_e32 v188, v188
	v_rcp_f32_e32 v189, v189
	v_rcp_f32_e32 v190, v190
	v_rcp_f32_e32 v191, v191
	v_rcp_f32_e32 v192, v192
	v_rcp_f32_e32 v193, v193
	v_rcp_f32_e32 v194, v194
	v_rcp_f32_e32 v195, v195
	v_pk_mul_f32 v[94:95], v[94:95], v[180:181]
	v_pk_mul_f32 v[96:97], v[96:97], v[182:183]
	v_pk_mul_f32 v[90:91], v[90:91], v[184:185]
	v_pk_mul_f32 v[92:93], v[92:93], v[186:187]
	v_pk_mul_f32 v[86:87], v[86:87], v[188:189]
	v_pk_mul_f32 v[88:89], v[88:89], v[190:191]
	v_pk_mul_f32 v[82:83], v[82:83], v[192:193]
	v_pk_mul_f32 v[84:85], v[84:85], v[194:195]
	v_pk_mul_f32 v[62:63], v[62:63], v[94:95]
	v_pk_mul_f32 v[64:65], v[64:65], v[96:97]
	v_pk_mul_f32 v[58:59], v[58:59], v[90:91]
	v_pk_mul_f32 v[60:61], v[60:61], v[92:93]
	v_pk_mul_f32 v[54:55], v[54:55], v[86:87]
	v_pk_mul_f32 v[56:57], v[56:57], v[88:89]
	v_pk_mul_f32 v[50:51], v[50:51], v[82:83]
	v_pk_mul_f32 v[52:53], v[52:53], v[84:85]
	v_cvt_pk_bf16_f32 v200, v62, v63
	v_cvt_pk_bf16_f32 v201, v64, v65
	v_cvt_pk_bf16_f32 v202, v58, v59
	v_cvt_pk_bf16_f32 v203, v60, v61
	v_add_u32_e32 v216, s4, v144
	v_mul_u32_u24_e32 v216, 0x1600, v216
	v_add_u32_e32 v216, v216, v142
	v_cvt_pk_bf16_f32 v204, v54, v55
	v_cvt_pk_bf16_f32 v205, v56, v57
	v_cvt_pk_bf16_f32 v206, v50, v51
	v_cvt_pk_bf16_f32 v207, v52, v53
	v_add_u32_e32 v217, s4, v146
	v_mul_u32_u24_e32 v217, 0x1600, v217
	v_add_u32_e32 v217, v217, v142
	global_store_dwordx4 v216, v[200:203], s[36:37]
	global_store_dwordx4 v217, v[204:207], s[36:37]
	v_pk_mul_f32 v[78:79], v[78:79], v[164:165] op_sel_hi:[1,0]
	v_pk_mul_f32 v[80:81], v[80:81], v[164:165] op_sel_hi:[1,0]
	v_pk_mul_f32 v[74:75], v[74:75], v[164:165] op_sel_hi:[1,0]
	v_pk_mul_f32 v[76:77], v[76:77], v[164:165] op_sel_hi:[1,0]
	v_pk_mul_f32 v[70:71], v[70:71], v[166:167] op_sel_hi:[1,0]
	v_pk_mul_f32 v[72:73], v[72:73], v[166:167] op_sel_hi:[1,0]
	v_pk_mul_f32 v[66:67], v[66:67], v[166:167] op_sel_hi:[1,0]
	v_pk_mul_f32 v[68:69], v[68:69], v[166:167] op_sel_hi:[1,0]
	v_pk_mul_f32 v[46:47], v[46:47], v[164:165] op_sel_hi:[1,0]
	v_pk_mul_f32 v[48:49], v[48:49], v[164:165] op_sel_hi:[1,0]
	v_pk_mul_f32 v[42:43], v[42:43], v[164:165] op_sel_hi:[1,0]
	v_pk_mul_f32 v[44:45], v[44:45], v[164:165] op_sel_hi:[1,0]
	v_pk_mul_f32 v[38:39], v[38:39], v[166:167] op_sel_hi:[1,0]
	v_pk_mul_f32 v[40:41], v[40:41], v[166:167] op_sel_hi:[1,0]
	v_pk_mul_f32 v[34:35], v[34:35], v[166:167] op_sel_hi:[1,0]
; #define LAS __attribute__((address_space(3)))
;     __device__ __forceinline__ void operator()(const f32x4 (&acc)[2][2][4][2], const Unit& u, const LAS float* rsl, int wr, int wc, int fr, int fq) const {
;         const int col0 = u.pn * 128 + wc * 32 + 8 * fq;
; #pragma unroll
;         for (int ai = 0; ai < 2; ++ai)
; #pragma unroll
;             for (int m = 0; m < 4; ++m) {
;                 const int rl = ai * HALF + wr * 64 + m * 16 + fr, row = u.pm * BM + rl;
;                 const float rs = rsl[rl];
;                 float o[8];
; #pragma unroll
;                 for (int n = 0; n < 2; ++n)
; #pragma unroll
;                     for (int e = 0; e < 4; ++e) {
;                         const float g = acc[ai][0][m][n][e] * rs, up = acc[ai][1][m][n][e] * rs;
;                         const float sg = g * __builtin_amdgcn_rcpf(1.0f + __builtin_amdgcn_exp2f(-g * LOG2E));
;                         o[n * 4 + e] = sg * up;
;                     }
;                 *(bf16x8*)(O + (size_t)row * DFF + col0) = pack8(o);
;             }
;     }
	v_pk_mul_f32 v[36:37], v[36:37], v[166:167] op_sel_hi:[1,0]
	v_pk_mul_f32 v[180:181], v[78:79], v[176:177] op_sel_hi:[1,0]
	v_pk_mul_f32 v[182:183], v[80:81], v[176:177] op_sel_hi:[1,0]
	v_pk_mul_f32 v[184:185], v[74:75], v[176:177] op_sel_hi:[1,0]
	v_pk_mul_f32 v[186:187], v[76:77], v[176:177] op_sel_hi:[1,0]
	v_pk_mul_f32 v[188:189], v[70:71], v[176:177] op_sel_hi:[1,0]
	v_pk_mul_f32 v[190:191], v[72:73], v[176:177] op_sel_hi:[1,0]
	v_pk_mul_f32 v[192:193], v[66:67], v[176:177] op_sel_hi:[1,0]
	v_pk_mul_f32 v[194:195], v[68:69], v[176:177] op_sel_hi:[1,0]
	v_exp_f32_e32 v180, v180
	v_exp_f32_e32 v181, v181
	v_exp_f32_e32 v182, v182
	v_exp_f32_e32 v183, v183
	v_exp_f32_e32 v184, v184
	v_exp_f32_e32 v185, v185
	v_exp_f32_e32 v186, v186
	v_exp_f32_e32 v187, v187
	v_exp_f32_e32 v188, v188
	v_exp_f32_e32 v189, v189
	v_exp_f32_e32 v190, v190
	v_exp_f32_e32 v191, v191
	v_exp_f32_e32 v192, v192
	v_exp_f32_e32 v193, v193
	v_exp_f32_e32 v194, v194
	v_exp_f32_e32 v195, v195
	v_pk_add_f32 v[180:181], v[180:181], v[178:179] op_sel_hi:[1,0]
	v_pk_add_f32 v[182:183], v[182:183], v[178:179] op_sel_hi:[1,0]
	v_pk_add_f32 v[184:185], v[184:185], v[178:179] op_sel_hi:[1,0]
	v_pk_add_f32 v[186:187], v[186:187], v[178:179] op_sel_hi:[1,0]
	v_pk_add_f32 v[188:189], v[188:189], v[178:179] op_sel_hi:[1,0]
	v_pk_add_f32 v[190:191], v[190:191], v[178:179] op_sel_hi:[1,0]
	v_pk_add_f32 v[192:193], v[192:193], v[178:179] op_sel_hi:[1,0]
	v_pk_add_f32 v[194:195], v[194:195], v[178:179] op_sel_hi:[1,0]
	v_rcp_f32_e32 v180, v180
	v_rcp_f32_e32 v181, v181
	v_rcp_f32_e32 v182, v182
	v_rcp_f32_e32 v183, v183
	v_rcp_f32_e32 v184, v184
	v_rcp_f32_e32 v185, v185
	v_rcp_f32_e32 v186, v186
	v_rcp_f32_e32 v187, v187
	v_rcp_f32_e32 v188, v188
	v_rcp_f32_e32 v189, v189
	v_rcp_f32_e32 v190, v190
	v_rcp_f32_e32 v191, v191
	v_rcp_f32_e32 v192, v192
	v_rcp_f32_e32 v193, v193
	v_rcp_f32_e32 v194, v194
	v_rcp_f32_e32 v195, v195
	v_pk_mul_f32 v[78:79], v[78:79], v[180:181]
	v_pk_mul_f32 v[80:81], v[80:81], v[182:183]
	v_pk_mul_f32 v[74:75], v[74:75], v[184:185]
	v_pk_mul_f32 v[76:77], v[76:77], v[186:187]
	v_pk_mul_f32 v[70:71], v[70:71], v[188:189]
	v_pk_mul_f32 v[72:73], v[72:73], v[190:191]
	v_pk_mul_f32 v[66:67], v[66:67], v[192:193]
	v_pk_mul_f32 v[68:69], v[68:69], v[194:195]
	v_pk_mul_f32 v[46:47], v[46:47], v[78:79]
	v_pk_mul_f32 v[48:49], v[48:49], v[80:81]
	v_pk_mul_f32 v[42:43], v[42:43], v[74:75]
	v_pk_mul_f32 v[44:45], v[44:45], v[76:77]
	v_pk_mul_f32 v[38:39], v[38:39], v[70:71]
	v_pk_mul_f32 v[40:41], v[40:41], v[72:73]
	v_pk_mul_f32 v[34:35], v[34:35], v[66:67]
	v_pk_mul_f32 v[36:37], v[36:37], v[68:69]
	v_cvt_pk_bf16_f32 v200, v46, v47
	v_cvt_pk_bf16_f32 v201, v48, v49
	v_cvt_pk_bf16_f32 v202, v42, v43
	v_cvt_pk_bf16_f32 v203, v44, v45
	v_add_u32_e32 v216, s4, v147
	v_mul_u32_u24_e32 v216, 0x1600, v216
	v_add_u32_e32 v216, v216, v142
	v_cvt_pk_bf16_f32 v204, v38, v39
	v_cvt_pk_bf16_f32 v205, v40, v41
	v_cvt_pk_bf16_f32 v206, v34, v35
	v_cvt_pk_bf16_f32 v207, v36, v37
	v_add_u32_e32 v217, s4, v148
	v_mul_u32_u24_e32 v217, 0x1600, v217
	v_add_u32_e32 v217, v217, v142
	global_store_dwordx4 v216, v[200:203], s[36:37]
	global_store_dwordx4 v217, v[204:207], s[36:37]
	v_pk_mul_f32 v[30:31], v[30:31], v[168:169] op_sel_hi:[1,0]
	v_pk_mul_f32 v[32:33], v[32:33], v[168:169] op_sel_hi:[1,0]
	v_pk_mul_f32 v[26:27], v[26:27], v[168:169] op_sel_hi:[1,0]
	v_pk_mul_f32 v[28:29], v[28:29], v[168:169] op_sel_hi:[1,0]
	v_pk_mul_f32 v[22:23], v[22:23], v[170:171] op_sel_hi:[1,0]
	v_pk_mul_f32 v[24:25], v[24:25], v[170:171] op_sel_hi:[1,0]
	v_pk_mul_f32 v[18:19], v[18:19], v[170:171] op_sel_hi:[1,0]
	v_pk_mul_f32 v[20:21], v[20:21], v[170:171] op_sel_hi:[1,0]
	v_pk_mul_f32 v[98:99], v[98:99], v[168:169] op_sel_hi:[1,0]
	v_pk_mul_f32 v[100:101], v[100:101], v[168:169] op_sel_hi:[1,0]
	v_pk_mul_f32 v[102:103], v[102:103], v[168:169] op_sel_hi:[1,0]
	v_pk_mul_f32 v[104:105], v[104:105], v[168:169] op_sel_hi:[1,0]
	v_pk_mul_f32 v[106:107], v[106:107], v[170:171] op_sel_hi:[1,0]
	v_pk_mul_f32 v[108:109], v[108:109], v[170:171] op_sel_hi:[1,0]
	v_pk_mul_f32 v[110:111], v[110:111], v[170:171] op_sel_hi:[1,0]
	v_pk_mul_f32 v[112:113], v[112:113], v[170:171] op_sel_hi:[1,0]
	v_pk_mul_f32 v[180:181], v[30:31], v[176:177] op_sel_hi:[1,0]
	v_pk_mul_f32 v[182:183], v[32:33], v[176:177] op_sel_hi:[1,0]
	v_pk_mul_f32 v[184:185], v[26:27], v[176:177] op_sel_hi:[1,0]
	v_pk_mul_f32 v[186:187], v[28:29], v[176:177] op_sel_hi:[1,0]
	v_pk_mul_f32 v[188:189], v[22:23], v[176:177] op_sel_hi:[1,0]
	v_pk_mul_f32 v[190:191], v[24:25], v[176:177] op_sel_hi:[1,0]
	v_pk_mul_f32 v[192:193], v[18:19], v[176:177] op_sel_hi:[1,0]
	v_pk_mul_f32 v[194:195], v[20:21], v[176:177] op_sel_hi:[1,0]
	v_exp_f32_e32 v180, v180
	v_exp_f32_e32 v181, v181
	v_exp_f32_e32 v182, v182
	v_exp_f32_e32 v183, v183
	v_exp_f32_e32 v184, v184
	v_exp_f32_e32 v185, v185
	v_exp_f32_e32 v186, v186
	v_exp_f32_e32 v187, v187
	v_exp_f32_e32 v188, v188
	v_exp_f32_e32 v189, v189
	v_exp_f32_e32 v190, v190
	v_exp_f32_e32 v191, v191
	v_exp_f32_e32 v192, v192
	v_exp_f32_e32 v193, v193
	v_exp_f32_e32 v194, v194
	v_exp_f32_e32 v195, v195
	v_pk_add_f32 v[180:181], v[180:181], v[178:179] op_sel_hi:[1,0]
	v_pk_add_f32 v[182:183], v[182:183], v[178:179] op_sel_hi:[1,0]
	v_pk_add_f32 v[184:185], v[184:185], v[178:179] op_sel_hi:[1,0]
	v_pk_add_f32 v[186:187], v[186:187], v[178:179] op_sel_hi:[1,0]
	v_pk_add_f32 v[188:189], v[188:189], v[178:179] op_sel_hi:[1,0]
	v_pk_add_f32 v[190:191], v[190:191], v[178:179] op_sel_hi:[1,0]
	v_pk_add_f32 v[192:193], v[192:193], v[178:179] op_sel_hi:[1,0]
	v_pk_add_f32 v[194:195], v[194:195], v[178:179] op_sel_hi:[1,0]
; #define LAS __attribute__((address_space(3)))
; #define PG8_BAR __builtin_amdgcn_s_barrier()
;     __device__ __forceinline__ void operator()(const f32x4 (&acc)[2][2][4][2], const Unit& u, const LAS float* rsl, int wr, int wc, int fr, int fq) const {
;         const int col0 = u.pn * 128 + wc * 32 + 8 * fq;
; #pragma unroll
;         for (int ai = 0; ai < 2; ++ai)
; #pragma unroll
;             for (int m = 0; m < 4; ++m) {
;                 const int rl = ai * HALF + wr * 64 + m * 16 + fr, row = u.pm * BM + rl;
;                 const float rs = rsl[rl];
;                 float o[8];
; #pragma unroll
;                 for (int n = 0; n < 2; ++n)
; #pragma unroll
;                     for (int e = 0; e < 4; ++e) {
;                         const float g = acc[ai][0][m][n][e] * rs, up = acc[ai][1][m][n][e] * rs;
;                         const float sg = g * __builtin_amdgcn_rcpf(1.0f + __builtin_amdgcn_exp2f(-g * LOG2E));
;                         o[n * 4 + e] = sg * up;
;                     }
;                 *(bf16x8*)(O + (size_t)row * DFF + col0) = pack8(o);
;             }
;     }
; template <class Epi>
; __device__ __forceinline__ void gemm_phase(LAS unsigned char* lds, const Gemm g, const StaticOrder& S, const Epi& E, const float* SS) {
;     ...
;         if (wr == 0) PG8_BAR;
;         E(acc, cur, rsl + ui * 256, wr, wc, fr, fq);
;         if (!has_next) break;
	v_rcp_f32_e32 v180, v180
	v_rcp_f32_e32 v181, v181
	v_rcp_f32_e32 v182, v182
	v_rcp_f32_e32 v183, v183
	v_rcp_f32_e32 v184, v184
	v_rcp_f32_e32 v185, v185
	v_rcp_f32_e32 v186, v186
	v_rcp_f32_e32 v187, v187
	v_rcp_f32_e32 v188, v188
	v_rcp_f32_e32 v189, v189
	v_rcp_f32_e32 v190, v190
	v_rcp_f32_e32 v191, v191
	v_rcp_f32_e32 v192, v192
	v_rcp_f32_e32 v193, v193
	v_rcp_f32_e32 v194, v194
	v_rcp_f32_e32 v195, v195
	v_pk_mul_f32 v[30:31], v[30:31], v[180:181]
	v_pk_mul_f32 v[32:33], v[32:33], v[182:183]
	v_pk_mul_f32 v[26:27], v[26:27], v[184:185]
	v_pk_mul_f32 v[28:29], v[28:29], v[186:187]
	v_pk_mul_f32 v[22:23], v[22:23], v[188:189]
	v_pk_mul_f32 v[24:25], v[24:25], v[190:191]
	v_pk_mul_f32 v[18:19], v[18:19], v[192:193]
	v_pk_mul_f32 v[20:21], v[20:21], v[194:195]
	v_pk_mul_f32 v[98:99], v[98:99], v[30:31]
	v_pk_mul_f32 v[100:101], v[100:101], v[32:33]
	v_pk_mul_f32 v[102:103], v[102:103], v[26:27]
	v_pk_mul_f32 v[104:105], v[104:105], v[28:29]
	v_pk_mul_f32 v[106:107], v[106:107], v[22:23]
	v_pk_mul_f32 v[108:109], v[108:109], v[24:25]
	v_pk_mul_f32 v[110:111], v[110:111], v[18:19]
	v_pk_mul_f32 v[112:113], v[112:113], v[20:21]
	v_cvt_pk_bf16_f32 v200, v98, v99
	v_cvt_pk_bf16_f32 v201, v100, v101
	v_cvt_pk_bf16_f32 v202, v102, v103
	v_cvt_pk_bf16_f32 v203, v104, v105
	v_add_u32_e32 v216, s4, v149
	v_mul_u32_u24_e32 v216, 0x1600, v216
	v_add_u32_e32 v216, v216, v142
	v_cvt_pk_bf16_f32 v204, v106, v107
	v_cvt_pk_bf16_f32 v205, v108, v109
	v_cvt_pk_bf16_f32 v206, v110, v111
	v_cvt_pk_bf16_f32 v207, v112, v113
	v_add_u32_e32 v217, s4, v150
	v_mul_u32_u24_e32 v217, 0x1600, v217
	v_add_u32_e32 v217, v217, v142
	global_store_dwordx4 v216, v[200:203], s[36:37]
	global_store_dwordx4 v217, v[204:207], s[36:37]
	v_pk_mul_f32 v[14:15], v[14:15], v[172:173] op_sel_hi:[1,0]
	v_pk_mul_f32 v[16:17], v[16:17], v[172:173] op_sel_hi:[1,0]
	v_pk_mul_f32 v[10:11], v[10:11], v[172:173] op_sel_hi:[1,0]
	v_pk_mul_f32 v[12:13], v[12:13], v[172:173] op_sel_hi:[1,0]
	v_pk_mul_f32 v[6:7], v[6:7], v[174:175] op_sel_hi:[1,0]
	v_pk_mul_f32 v[8:9], v[8:9], v[174:175] op_sel_hi:[1,0]
	v_pk_mul_f32 v[2:3], v[2:3], v[174:175] op_sel_hi:[1,0]
	v_pk_mul_f32 v[4:5], v[4:5], v[174:175] op_sel_hi:[1,0]
	v_pk_mul_f32 v[114:115], v[114:115], v[172:173] op_sel_hi:[1,0]
	v_pk_mul_f32 v[116:117], v[116:117], v[172:173] op_sel_hi:[1,0]
	v_pk_mul_f32 v[118:119], v[118:119], v[172:173] op_sel_hi:[1,0]
	v_pk_mul_f32 v[120:121], v[120:121], v[172:173] op_sel_hi:[1,0]
	v_pk_mul_f32 v[122:123], v[122:123], v[174:175] op_sel_hi:[1,0]
	v_pk_mul_f32 v[124:125], v[124:125], v[174:175] op_sel_hi:[1,0]
	v_pk_mul_f32 v[126:127], v[126:127], v[174:175] op_sel_hi:[1,0]
	v_pk_mul_f32 v[128:129], v[128:129], v[174:175] op_sel_hi:[1,0]
	v_pk_mul_f32 v[180:181], v[14:15], v[176:177] op_sel_hi:[1,0]
	v_pk_mul_f32 v[182:183], v[16:17], v[176:177] op_sel_hi:[1,0]
	v_pk_mul_f32 v[184:185], v[10:11], v[176:177] op_sel_hi:[1,0]
	v_pk_mul_f32 v[186:187], v[12:13], v[176:177] op_sel_hi:[1,0]
	v_pk_mul_f32 v[188:189], v[6:7], v[176:177] op_sel_hi:[1,0]
	v_pk_mul_f32 v[190:191], v[8:9], v[176:177] op_sel_hi:[1,0]
	v_pk_mul_f32 v[192:193], v[2:3], v[176:177] op_sel_hi:[1,0]
	v_pk_mul_f32 v[194:195], v[4:5], v[176:177] op_sel_hi:[1,0]
	v_exp_f32_e32 v180, v180
	v_exp_f32_e32 v181, v181
	v_exp_f32_e32 v182, v182
	v_exp_f32_e32 v183, v183
	v_exp_f32_e32 v184, v184
	v_exp_f32_e32 v185, v185
	v_exp_f32_e32 v186, v186
	v_exp_f32_e32 v187, v187
	v_exp_f32_e32 v188, v188
	v_exp_f32_e32 v189, v189
	v_exp_f32_e32 v190, v190
	v_exp_f32_e32 v191, v191
	v_exp_f32_e32 v192, v192
	v_exp_f32_e32 v193, v193
	v_exp_f32_e32 v194, v194
	v_exp_f32_e32 v195, v195
	v_pk_add_f32 v[180:181], v[180:181], v[178:179] op_sel_hi:[1,0]
	v_pk_add_f32 v[182:183], v[182:183], v[178:179] op_sel_hi:[1,0]
	v_pk_add_f32 v[184:185], v[184:185], v[178:179] op_sel_hi:[1,0]
	v_pk_add_f32 v[186:187], v[186:187], v[178:179] op_sel_hi:[1,0]
	v_pk_add_f32 v[188:189], v[188:189], v[178:179] op_sel_hi:[1,0]
	v_pk_add_f32 v[190:191], v[190:191], v[178:179] op_sel_hi:[1,0]
	v_pk_add_f32 v[192:193], v[192:193], v[178:179] op_sel_hi:[1,0]
	v_pk_add_f32 v[194:195], v[194:195], v[178:179] op_sel_hi:[1,0]
	v_rcp_f32_e32 v180, v180
	v_rcp_f32_e32 v181, v181
	v_rcp_f32_e32 v182, v182
	v_rcp_f32_e32 v183, v183
	v_rcp_f32_e32 v184, v184
	v_rcp_f32_e32 v185, v185
	v_rcp_f32_e32 v186, v186
	v_rcp_f32_e32 v187, v187
	v_rcp_f32_e32 v188, v188
	v_rcp_f32_e32 v189, v189
	v_rcp_f32_e32 v190, v190
	v_rcp_f32_e32 v191, v191
	v_rcp_f32_e32 v192, v192
	v_rcp_f32_e32 v193, v193
	v_rcp_f32_e32 v194, v194
	v_rcp_f32_e32 v195, v195
	v_pk_mul_f32 v[14:15], v[14:15], v[180:181]
	v_pk_mul_f32 v[16:17], v[16:17], v[182:183]
	v_pk_mul_f32 v[10:11], v[10:11], v[184:185]
	v_pk_mul_f32 v[12:13], v[12:13], v[186:187]
	v_pk_mul_f32 v[6:7], v[6:7], v[188:189]
	v_pk_mul_f32 v[8:9], v[8:9], v[190:191]
	v_pk_mul_f32 v[2:3], v[2:3], v[192:193]
	v_pk_mul_f32 v[4:5], v[4:5], v[194:195]
	v_pk_mul_f32 v[114:115], v[114:115], v[14:15]
	v_pk_mul_f32 v[116:117], v[116:117], v[16:17]
	v_pk_mul_f32 v[118:119], v[118:119], v[10:11]
	v_pk_mul_f32 v[120:121], v[120:121], v[12:13]
	v_pk_mul_f32 v[122:123], v[122:123], v[6:7]
	v_pk_mul_f32 v[124:125], v[124:125], v[8:9]
	v_pk_mul_f32 v[126:127], v[126:127], v[2:3]
	v_pk_mul_f32 v[128:129], v[128:129], v[4:5]
	v_cvt_pk_bf16_f32 v200, v114, v115
	v_cvt_pk_bf16_f32 v201, v116, v117
	v_cvt_pk_bf16_f32 v202, v118, v119
	v_cvt_pk_bf16_f32 v203, v120, v121
	v_add_u32_e32 v216, s4, v151
	v_mul_u32_u24_e32 v216, 0x1600, v216
	v_add_u32_e32 v216, v216, v142
	v_cvt_pk_bf16_f32 v204, v122, v123
	v_cvt_pk_bf16_f32 v205, v124, v125
	v_cvt_pk_bf16_f32 v206, v126, v127
	v_cvt_pk_bf16_f32 v207, v128, v129
	v_add_u32_e32 v217, s4, v152
	v_mul_u32_u24_e32 v217, 0x1600, v217
	v_add_u32_e32 v217, v217, v142
	global_store_dwordx4 v216, v[200:203], s[36:37]
	global_store_dwordx4 v217, v[204:207], s[36:37]
	s_andn2_b64 vcc, exec, s[2:3]
	s_cbranch_vccnz .LBB0_386
	s_andn2_b64 vcc, exec, s[20:21]
	s_cbranch_vccnz .LBB0_372
	s_barrier
	s_branch .LBB0_372

; #define LAS __attribute__((address_space(3)))
;     __device__ __forceinline__ void operator()(const f32x4 (&acc)[2][2][4][2], const Unit& u, const LAS float* rsl, int wr, int wc, int fr, int fq) const {
;         bf16_t* base = XB + (size_t)(u.pm * BM + wr * 64 + fr) * D + u.pn * BM + wc * 32 + 8 * fq;
;         bf16x8 xin[2][4][2];
; #pragma unroll
;         for (int ai = 0; ai < 2; ++ai)
; #pragma unroll
;             for (int m = 0; m < 4; ++m)
; #pragma unroll
;                 for (int bj = 0; bj < 2; ++bj) xin[ai][m][bj] = *(const bf16x8*)(base + (size_t)(ai * HALF + m * 16) * D + bj * HALF);
; #pragma unroll
;         for (int ai = 0; ai < 2; ++ai)
; #pragma unroll
;             for (int m = 0; m < 4; ++m) {
;                 const int row = u.pm * BM + ai * HALF + wr * 64 + m * 16 + fr;
;                 float ss = 0.f;
; #pragma unroll
;                 for (int bj = 0; bj < 2; ++bj) {
;                     float xf[8]; unpack8(xin[ai][m][bj], xf);
;                     f32x4 x0 = (f32x4){xf[0], xf[1], xf[2], xf[3]}, x1 = (f32x4){xf[4], xf[5], xf[6], xf[7]};
;                     x0 += acc[ai][bj][m][0] * s; x1 += acc[ai][bj][m][1] * s;
;                     *(bf16x8*)(base + (size_t)(ai * HALF + m * 16) * D + bj * HALF) = pack8v(x0, x1);
;                     ss += (x0[0] * x0[0] + x0[1] * x0[1]) + (x0[2] * x0[2] + x0[3] * x0[3]) + (x1[0] * x1[0] + x1[1] * x1[1]) + (x1[2] * x1[2] + x1[3] * x1[3]);
.LBB0_643:
	v_lshl_add_u32 v204, s59, 8, v229
	v_ashrrev_i32_e32 v205, 31, v204
	v_lshlrev_b64 v[106:107], 11, v[204:205]
	s_lshl_b32 s42, s58, 8
	v_lshl_add_u64 v[106:107], s[8:9], 0, v[106:107]
	s_ashr_i32 s43, s42, 31
	v_lshl_add_u64 v[106:107], s[42:43], 1, v[106:107]
	v_lshl_add_u64 v[106:107], v[106:107], 0, s[62:63]
	v_lshl_add_u64 v[206:207], v[106:107], 0, v[0:1]
	v_lshrrev_b32_e32 v222, 2, v210
	v_and_b32_e32 v223, 15, v210
	v_sub_u32_e32 v222, v222, v223
	v_lshlrev_b32_e32 v222, 11, v222
	v_and_b32_e32 v223, 3, v210
	v_lshrrev_b32_e32 v224, 4, v210
	v_sub_u32_e32 v223, v223, v224
	v_lshl_add_u32 v222, v223, 4, v222
	v_ashrrev_i32_e32 v223, 31, v222
	v_lshl_add_u64 v[206:207], v[206:207], 0, v[222:223]
	v_and_b32_e32 v228, 15, v210
	v_lshl_add_u32 v228, v228, 2, v224
	v_lshlrev_b32_e32 v228, 2, v228
	v_and_b32_e32 v224, 3, v210
	v_lshrrev_b32_e32 v229, 2, v210
	v_lshl_add_u32 v229, v224, 4, v229
	v_lshlrev_b32_e32 v229, 2, v229
	global_load_dwordx4 v[216:219], v[206:207], off
	global_load_dwordx4 v[186:189], v[206:207], off offset:256
	v_add_co_u32_e32 v220, vcc, s97, v206
	s_nop 1
	v_addc_co_u32_e32 v221, vcc, 0, v207, vcc
	global_load_dwordx4 v[182:185], v[220:221], off
	global_load_dwordx4 v[178:181], v[220:221], off offset:256
	v_add_co_u32_e32 v220, vcc, s81, v206
	s_nop 1
	v_addc_co_u32_e32 v221, vcc, 0, v207, vcc
	global_load_dwordx4 v[174:177], v[220:221], off
	global_load_dwordx4 v[170:173], v[220:221], off offset:256
	v_add_co_u32_e32 v220, vcc, s33, v206
	s_nop 1
	v_addc_co_u32_e32 v221, vcc, 0, v207, vcc
	global_load_dwordx4 v[166:169], v[220:221], off
	global_load_dwordx4 v[162:165], v[220:221], off offset:256
	v_add_co_u32_e32 v220, vcc, s91, v206
	s_nop 1
	v_addc_co_u32_e32 v221, vcc, 0, v207, vcc
	global_load_dwordx4 v[150:153], v[220:221], off
	global_load_dwordx4 v[146:149], v[220:221], off offset:256
	v_add_co_u32_e32 v220, vcc, s84, v206
	s_nop 1
	v_addc_co_u32_e32 v221, vcc, 0, v207, vcc
	global_load_dwordx4 v[142:145], v[220:221], off
	global_load_dwordx4 v[138:141], v[220:221], off offset:256
	v_add_co_u32_e32 v220, vcc, s85, v206
	s_nop 1
	v_addc_co_u32_e32 v221, vcc, 0, v207, vcc
	global_load_dwordx4 v[126:129], v[220:221], off
	global_load_dwordx4 v[122:125], v[220:221], off offset:256
	v_add_co_u32_e32 v220, vcc, s90, v206
	s_nop 1
	v_addc_co_u32_e32 v221, vcc, 0, v207, vcc
	global_load_dwordx4 v[110:113], v[220:221], off
	global_load_dwordx4 v[106:109], v[220:221], off offset:256
	v_readlane_b32 s68, v255, 12
	s_waitcnt vmcnt(14)
	ds_bpermute_b32 v216, v228, v216
	ds_bpermute_b32 v217, v228, v217
	ds_bpermute_b32 v218, v228, v218
	ds_bpermute_b32 v219, v228, v219
	ds_bpermute_b32 v186, v228, v186
	ds_bpermute_b32 v187, v228, v187
	ds_bpermute_b32 v188, v228, v188
	ds_bpermute_b32 v189, v228, v189
	s_waitcnt vmcnt(12)
	ds_bpermute_b32 v182, v228, v182
	ds_bpermute_b32 v183, v228, v183
	ds_bpermute_b32 v184, v228, v184
	ds_bpermute_b32 v185, v228, v185
	ds_bpermute_b32 v178, v228, v178
	ds_bpermute_b32 v179, v228, v179
	ds_bpermute_b32 v180, v228, v180
	ds_bpermute_b32 v181, v228, v181
	s_waitcnt lgkmcnt(8)
	v_lshlrev_b32_e32 v222, 16, v216
	v_and_b32_e32 v223, 0xffff0000, v216
	v_lshlrev_b32_e32 v224, 16, v217
	v_and_b32_e32 v225, 0xffff0000, v217
	v_pk_fma_f32 v[158:159], s[24:25], v[158:159], v[222:223]
	v_pk_fma_f32 v[160:161], s[24:25], v[160:161], v[224:225]
	v_lshlrev_b32_e32 v222, 16, v218
	v_and_b32_e32 v223, 0xffff0000, v218
	v_lshlrev_b32_e32 v224, 16, v219
	v_and_b32_e32 v225, 0xffff0000, v219
	v_pk_fma_f32 v[154:155], s[24:25], v[154:155], v[222:223]
	v_pk_fma_f32 v[156:157], s[24:25], v[156:157], v[224:225]
	v_cvt_pk_bf16_f32 v216, v158, v159
	v_mul_f32_e32 v226, v159, v159
	v_mul_f32_e32 v222, v161, v161
	v_cvt_pk_bf16_f32 v217, v160, v161
	v_fmac_f32_e32 v226, v158, v158
	v_fmac_f32_e32 v222, v160, v160
	v_cvt_pk_bf16_f32 v218, v154, v155
	v_add_f32_e32 v226, v226, v222
	v_mul_f32_e32 v222, v155, v155
	v_cvt_pk_bf16_f32 v219, v156, v157
	v_fmac_f32_e32 v222, v154, v154
	v_mul_f32_e32 v223, v157, v157
	v_add_f32_e32 v226, v222, v226
	v_fmac_f32_e32 v223, v156, v156
	v_add_f32_e32 v226, v223, v226
	v_lshlrev_b32_e32 v222, 16, v186
	v_and_b32_e32 v223, 0xffff0000, v186
	v_lshlrev_b32_e32 v224, 16, v187
	v_and_b32_e32 v225, 0xffff0000, v187
	v_pk_fma_f32 v[134:135], s[24:25], v[134:135], v[222:223]
	v_pk_fma_f32 v[136:137], s[24:25], v[136:137], v[224:225]
	v_lshlrev_b32_e32 v222, 16, v188
	v_and_b32_e32 v223, 0xffff0000, v188
	v_lshlrev_b32_e32 v224, 16, v189
	v_and_b32_e32 v225, 0xffff0000, v189
	v_pk_fma_f32 v[130:131], s[24:25], v[130:131], v[222:223]
	v_pk_fma_f32 v[132:133], s[24:25], v[132:133], v[224:225]
	v_cvt_pk_bf16_f32 v186, v134, v135
	v_mul_f32_e32 v227, v135, v135
	v_mul_f32_e32 v222, v137, v137
	v_cvt_pk_bf16_f32 v187, v136, v137
	v_fmac_f32_e32 v227, v134, v134
	v_fmac_f32_e32 v222, v136, v136
	v_cvt_pk_bf16_f32 v188, v130, v131
	v_add_f32_e32 v227, v227, v222
	v_mul_f32_e32 v222, v131, v131
	v_cvt_pk_bf16_f32 v189, v132, v133
	v_fmac_f32_e32 v222, v130, v130
	v_mul_f32_e32 v223, v133, v133
	v_add_f32_e32 v227, v222, v227
	v_fmac_f32_e32 v223, v132, v132
	v_add_f32_e32 v227, v223, v227
	ds_bpermute_b32 v216, v229, v216
	ds_bpermute_b32 v217, v229, v217
	ds_bpermute_b32 v218, v229, v218
	ds_bpermute_b32 v219, v229, v219
	ds_bpermute_b32 v186, v229, v186
	ds_bpermute_b32 v187, v229, v187
	ds_bpermute_b32 v188, v229, v188
	ds_bpermute_b32 v189, v229, v189
	v_add_f32_e32 v134, v226, v227
	s_waitcnt vmcnt(10)
	ds_bpermute_b32 v174, v228, v174
	ds_bpermute_b32 v175, v228, v175
	ds_bpermute_b32 v176, v228, v176
	ds_bpermute_b32 v177, v228, v177
	ds_bpermute_b32 v170, v228, v170
	ds_bpermute_b32 v171, v228, v171
	ds_bpermute_b32 v172, v228, v172
	ds_bpermute_b32 v173, v228, v173
	s_waitcnt lgkmcnt(8)
;     __device__ __forceinline__ void operator()(const f32x4 (&acc)[2][2][4][2], const Unit& u, const LAS float* rsl, int wr, int wc, int fr, int fq) const {
;     ...
;                 for (int bj = 0; bj < 2; ++bj) xin[ai][m][bj] = *(const bf16x8*)(base + (size_t)(ai * HALF + m * 16) * D + bj * HALF);
; #pragma unroll
;         for (int ai = 0; ai < 2; ++ai)
; #pragma unroll
;             for (int m = 0; m < 4; ++m) {
;                 const int row = u.pm * BM + ai * HALF + wr * 64 + m * 16 + fr;
;                 float ss = 0.f;
; #pragma unroll
;                 for (int bj = 0; bj < 2; ++bj) {
;                     float xf[8]; unpack8(xin[ai][m][bj], xf);
;                     f32x4 x0 = (f32x4){xf[0], xf[1], xf[2], xf[3]}, x1 = (f32x4){xf[4], xf[5], xf[6], xf[7]};
;                     x0 += acc[ai][bj][m][0] * s; x1 += acc[ai][bj][m][1] * s;
;                     *(bf16x8*)(base + (size_t)(ai * HALF + m * 16) * D + bj * HALF) = pack8v(x0, x1);
;                     ss += (x0[0] * x0[0] + x0[1] * x0[1]) + (x0[2] * x0[2] + x0[3] * x0[3]) + (x1[0] * x1[0] + x1[1] * x1[1]) + (x1[2] * x1[2] + x1[3] * x1[3]);
	global_store_dwordx4 v[206:207], v[216:219], off
	global_store_dwordx4 v[206:207], v[186:189], off offset:256
	v_lshlrev_b32_e32 v222, 16, v182
	v_and_b32_e32 v223, 0xffff0000, v182
	v_lshlrev_b32_e32 v224, 16, v183
	v_and_b32_e32 v225, 0xffff0000, v183
	v_pk_fma_f32 v[118:119], s[24:25], v[118:119], v[222:223]
	v_pk_fma_f32 v[120:121], s[24:25], v[120:121], v[224:225]
	v_lshlrev_b32_e32 v222, 16, v184
	v_and_b32_e32 v223, 0xffff0000, v184
	v_lshlrev_b32_e32 v224, 16, v185
	v_and_b32_e32 v225, 0xffff0000, v185
	v_pk_fma_f32 v[114:115], s[24:25], v[114:115], v[222:223]
	v_pk_fma_f32 v[116:117], s[24:25], v[116:117], v[224:225]
	v_cvt_pk_bf16_f32 v182, v118, v119
	v_mul_f32_e32 v226, v119, v119
	v_mul_f32_e32 v222, v121, v121
	v_cvt_pk_bf16_f32 v183, v120, v121
	v_fmac_f32_e32 v226, v118, v118
	v_fmac_f32_e32 v222, v120, v120
	v_cvt_pk_bf16_f32 v184, v114, v115
	v_add_f32_e32 v226, v226, v222
	v_mul_f32_e32 v222, v115, v115
	v_cvt_pk_bf16_f32 v185, v116, v117
	v_fmac_f32_e32 v222, v114, v114
	v_mul_f32_e32 v223, v117, v117
	v_add_f32_e32 v226, v222, v226
	v_fmac_f32_e32 v223, v116, v116
	v_add_f32_e32 v226, v223, v226
	v_lshlrev_b32_e32 v222, 16, v178
	v_and_b32_e32 v223, 0xffff0000, v178
	v_lshlrev_b32_e32 v224, 16, v179
	v_and_b32_e32 v225, 0xffff0000, v179
	v_pk_fma_f32 v[102:103], s[24:25], v[102:103], v[222:223]
	v_pk_fma_f32 v[104:105], s[24:25], v[104:105], v[224:225]
	v_lshlrev_b32_e32 v222, 16, v180
	v_and_b32_e32 v223, 0xffff0000, v180
	v_lshlrev_b32_e32 v224, 16, v181
	v_and_b32_e32 v225, 0xffff0000, v181
	v_pk_fma_f32 v[98:99], s[24:25], v[98:99], v[222:223]
	v_pk_fma_f32 v[100:101], s[24:25], v[100:101], v[224:225]
	v_cvt_pk_bf16_f32 v178, v102, v103
	v_mul_f32_e32 v227, v103, v103
	v_mul_f32_e32 v222, v105, v105
	v_cvt_pk_bf16_f32 v179, v104, v105
	v_fmac_f32_e32 v227, v102, v102
	v_fmac_f32_e32 v222, v104, v104
	v_cvt_pk_bf16_f32 v180, v98, v99
	v_add_f32_e32 v227, v227, v222
	v_mul_f32_e32 v222, v99, v99
	v_cvt_pk_bf16_f32 v181, v100, v101
	v_fmac_f32_e32 v222, v98, v98
	v_mul_f32_e32 v223, v101, v101
	v_add_f32_e32 v227, v222, v227
	v_fmac_f32_e32 v223, v100, v100
	v_add_f32_e32 v227, v223, v227
	ds_bpermute_b32 v182, v229, v182
	ds_bpermute_b32 v183, v229, v183
	ds_bpermute_b32 v184, v229, v184
	ds_bpermute_b32 v185, v229, v185
	ds_bpermute_b32 v178, v229, v178
	ds_bpermute_b32 v179, v229, v179
	ds_bpermute_b32 v180, v229, v180
	ds_bpermute_b32 v181, v229, v181
	v_add_f32_e32 v102, v226, v227
	s_waitcnt vmcnt(10)
	ds_bpermute_b32 v166, v228, v166
	ds_bpermute_b32 v167, v228, v167
	ds_bpermute_b32 v168, v228, v168
	ds_bpermute_b32 v169, v228, v169
	ds_bpermute_b32 v162, v228, v162
	ds_bpermute_b32 v163, v228, v163
	ds_bpermute_b32 v164, v228, v164
	ds_bpermute_b32 v165, v228, v165
	s_waitcnt lgkmcnt(8)
	v_add_co_u32_e32 v220, vcc, s97, v206
	s_nop 1
	v_addc_co_u32_e32 v221, vcc, 0, v207, vcc
	global_store_dwordx4 v[220:221], v[182:185], off
	global_store_dwordx4 v[220:221], v[178:181], off offset:256
	v_lshlrev_b32_e32 v222, 16, v174
	v_and_b32_e32 v223, 0xffff0000, v174
	v_lshlrev_b32_e32 v224, 16, v175
	v_and_b32_e32 v225, 0xffff0000, v175
	v_pk_fma_f32 v[94:95], s[24:25], v[94:95], v[222:223]
	v_pk_fma_f32 v[96:97], s[24:25], v[96:97], v[224:225]
	v_lshlrev_b32_e32 v222, 16, v176
	v_and_b32_e32 v223, 0xffff0000, v176
	v_lshlrev_b32_e32 v224, 16, v177
	v_and_b32_e32 v225, 0xffff0000, v177
	v_pk_fma_f32 v[90:91], s[24:25], v[90:91], v[222:223]
	v_pk_fma_f32 v[92:93], s[24:25], v[92:93], v[224:225]
	v_cvt_pk_bf16_f32 v174, v94, v95
	v_mul_f32_e32 v226, v95, v95
	v_mul_f32_e32 v222, v97, v97
	v_cvt_pk_bf16_f32 v175, v96, v97
	v_fmac_f32_e32 v226, v94, v94
	v_fmac_f32_e32 v222, v96, v96
	v_cvt_pk_bf16_f32 v176, v90, v91
	v_add_f32_e32 v226, v226, v222
	v_mul_f32_e32 v222, v91, v91
	v_cvt_pk_bf16_f32 v177, v92, v93
	v_fmac_f32_e32 v222, v90, v90
	v_mul_f32_e32 v223, v93, v93
	v_add_f32_e32 v226, v222, v226
	v_fmac_f32_e32 v223, v92, v92
	v_add_f32_e32 v226, v223, v226
	v_lshlrev_b32_e32 v222, 16, v170
	v_and_b32_e32 v223, 0xffff0000, v170
	v_lshlrev_b32_e32 v224, 16, v171
	v_and_b32_e32 v225, 0xffff0000, v171
	v_pk_fma_f32 v[86:87], s[24:25], v[86:87], v[222:223]
	v_pk_fma_f32 v[88:89], s[24:25], v[88:89], v[224:225]
	v_lshlrev_b32_e32 v222, 16, v172
	v_and_b32_e32 v223, 0xffff0000, v172
	v_lshlrev_b32_e32 v224, 16, v173
	v_and_b32_e32 v225, 0xffff0000, v173
	v_pk_fma_f32 v[82:83], s[24:25], v[82:83], v[222:223]
	v_pk_fma_f32 v[84:85], s[24:25], v[84:85], v[224:225]
	v_cvt_pk_bf16_f32 v170, v86, v87
	v_mul_f32_e32 v227, v87, v87
	v_mul_f32_e32 v222, v89, v89
	v_cvt_pk_bf16_f32 v171, v88, v89
	v_fmac_f32_e32 v227, v86, v86
	v_fmac_f32_e32 v222, v88, v88
	v_cvt_pk_bf16_f32 v172, v82, v83
	v_add_f32_e32 v227, v227, v222
	v_mul_f32_e32 v222, v83, v83
	v_cvt_pk_bf16_f32 v173, v84, v85
	v_fmac_f32_e32 v222, v82, v82
	v_mul_f32_e32 v223, v85, v85
	v_add_f32_e32 v227, v222, v227
	v_fmac_f32_e32 v223, v84, v84
	v_add_f32_e32 v227, v223, v227
	ds_bpermute_b32 v174, v229, v174
	ds_bpermute_b32 v175, v229, v175
	ds_bpermute_b32 v176, v229, v176
	ds_bpermute_b32 v177, v229, v177
	ds_bpermute_b32 v170, v229, v170
	ds_bpermute_b32 v171, v229, v171
	ds_bpermute_b32 v172, v229, v172
	ds_bpermute_b32 v173, v229, v173
	v_add_f32_e32 v86, v226, v227
	s_waitcnt vmcnt(10)
	ds_bpermute_b32 v150, v228, v150
	ds_bpermute_b32 v151, v228, v151
	ds_bpermute_b32 v152, v228, v152
	ds_bpermute_b32 v153, v228, v153
	ds_bpermute_b32 v146, v228, v146
	ds_bpermute_b32 v147, v228, v147
	ds_bpermute_b32 v148, v228, v148
	ds_bpermute_b32 v149, v228, v149
	s_waitcnt lgkmcnt(8)
;     __device__ __forceinline__ void operator()(const f32x4 (&acc)[2][2][4][2], const Unit& u, const LAS float* rsl, int wr, int wc, int fr, int fq) const {
;     ...
;                 for (int bj = 0; bj < 2; ++bj) xin[ai][m][bj] = *(const bf16x8*)(base + (size_t)(ai * HALF + m * 16) * D + bj * HALF);
; #pragma unroll
;         for (int ai = 0; ai < 2; ++ai)
; #pragma unroll
;             for (int m = 0; m < 4; ++m) {
;                 const int row = u.pm * BM + ai * HALF + wr * 64 + m * 16 + fr;
;                 float ss = 0.f;
; #pragma unroll
;                 for (int bj = 0; bj < 2; ++bj) {
;                     float xf[8]; unpack8(xin[ai][m][bj], xf);
;                     f32x4 x0 = (f32x4){xf[0], xf[1], xf[2], xf[3]}, x1 = (f32x4){xf[4], xf[5], xf[6], xf[7]};
;                     x0 += acc[ai][bj][m][0] * s; x1 += acc[ai][bj][m][1] * s;
;                     *(bf16x8*)(base + (size_t)(ai * HALF + m * 16) * D + bj * HALF) = pack8v(x0, x1);
;                     ss += (x0[0] * x0[0] + x0[1] * x0[1]) + (x0[2] * x0[2] + x0[3] * x0[3]) + (x1[0] * x1[0] + x1[1] * x1[1]) + (x1[2] * x1[2] + x1[3] * x1[3]);
	v_add_co_u32_e32 v220, vcc, s81, v206
	s_nop 1
	v_addc_co_u32_e32 v221, vcc, 0, v207, vcc
	global_store_dwordx4 v[220:221], v[174:177], off
	global_store_dwordx4 v[220:221], v[170:173], off offset:256
	v_lshlrev_b32_e32 v222, 16, v166
	v_and_b32_e32 v223, 0xffff0000, v166
	v_lshlrev_b32_e32 v224, 16, v167
	v_and_b32_e32 v225, 0xffff0000, v167
	v_pk_fma_f32 v[78:79], s[24:25], v[78:79], v[222:223]
	v_pk_fma_f32 v[80:81], s[24:25], v[80:81], v[224:225]
	v_lshlrev_b32_e32 v222, 16, v168
	v_and_b32_e32 v223, 0xffff0000, v168
	v_lshlrev_b32_e32 v224, 16, v169
	v_and_b32_e32 v225, 0xffff0000, v169
	v_pk_fma_f32 v[74:75], s[24:25], v[74:75], v[222:223]
	v_pk_fma_f32 v[76:77], s[24:25], v[76:77], v[224:225]
	v_cvt_pk_bf16_f32 v166, v78, v79
	v_mul_f32_e32 v226, v79, v79
	v_mul_f32_e32 v222, v81, v81
	v_cvt_pk_bf16_f32 v167, v80, v81
	v_fmac_f32_e32 v226, v78, v78
	v_fmac_f32_e32 v222, v80, v80
	v_cvt_pk_bf16_f32 v168, v74, v75
	v_add_f32_e32 v226, v226, v222
	v_mul_f32_e32 v222, v75, v75
	v_cvt_pk_bf16_f32 v169, v76, v77
	v_fmac_f32_e32 v222, v74, v74
	v_mul_f32_e32 v223, v77, v77
	v_add_f32_e32 v226, v222, v226
	v_fmac_f32_e32 v223, v76, v76
	v_add_f32_e32 v226, v223, v226
	v_lshlrev_b32_e32 v222, 16, v162
	v_and_b32_e32 v223, 0xffff0000, v162
	v_lshlrev_b32_e32 v224, 16, v163
	v_and_b32_e32 v225, 0xffff0000, v163
	v_pk_fma_f32 v[70:71], s[24:25], v[70:71], v[222:223]
	v_pk_fma_f32 v[72:73], s[24:25], v[72:73], v[224:225]
	v_lshlrev_b32_e32 v222, 16, v164
	v_and_b32_e32 v223, 0xffff0000, v164
	v_lshlrev_b32_e32 v224, 16, v165
	v_and_b32_e32 v225, 0xffff0000, v165
	v_pk_fma_f32 v[66:67], s[24:25], v[66:67], v[222:223]
	v_pk_fma_f32 v[68:69], s[24:25], v[68:69], v[224:225]
	v_cvt_pk_bf16_f32 v162, v70, v71
	v_mul_f32_e32 v227, v71, v71
	v_mul_f32_e32 v222, v73, v73
	v_cvt_pk_bf16_f32 v163, v72, v73
	v_fmac_f32_e32 v227, v70, v70
	v_fmac_f32_e32 v222, v72, v72
	v_cvt_pk_bf16_f32 v164, v66, v67
	v_add_f32_e32 v227, v227, v222
	v_mul_f32_e32 v222, v67, v67
	v_cvt_pk_bf16_f32 v165, v68, v69
	v_fmac_f32_e32 v222, v66, v66
	v_mul_f32_e32 v223, v69, v69
	v_add_f32_e32 v227, v222, v227
	v_fmac_f32_e32 v223, v68, v68
	v_add_f32_e32 v227, v223, v227
	ds_bpermute_b32 v166, v229, v166
	ds_bpermute_b32 v167, v229, v167
	ds_bpermute_b32 v168, v229, v168
	ds_bpermute_b32 v169, v229, v169
	ds_bpermute_b32 v162, v229, v162
	ds_bpermute_b32 v163, v229, v163
	ds_bpermute_b32 v164, v229, v164
	ds_bpermute_b32 v165, v229, v165
	v_add_f32_e32 v70, v226, v227
	s_waitcnt vmcnt(10)
	ds_bpermute_b32 v142, v228, v142
	ds_bpermute_b32 v143, v228, v143
	ds_bpermute_b32 v144, v228, v144
	ds_bpermute_b32 v145, v228, v145
	ds_bpermute_b32 v138, v228, v138
	ds_bpermute_b32 v139, v228, v139
	ds_bpermute_b32 v140, v228, v140
	ds_bpermute_b32 v141, v228, v141
	s_waitcnt lgkmcnt(8)
	v_add_co_u32_e32 v220, vcc, s33, v206
	s_nop 1
	v_addc_co_u32_e32 v221, vcc, 0, v207, vcc
	global_store_dwordx4 v[220:221], v[166:169], off
	global_store_dwordx4 v[220:221], v[162:165], off offset:256
	v_lshlrev_b32_e32 v222, 16, v150
	v_and_b32_e32 v223, 0xffff0000, v150
	v_lshlrev_b32_e32 v224, 16, v151
	v_and_b32_e32 v225, 0xffff0000, v151
	v_pk_fma_f32 v[62:63], s[24:25], v[62:63], v[222:223]
	v_pk_fma_f32 v[64:65], s[24:25], v[64:65], v[224:225]
	v_lshlrev_b32_e32 v222, 16, v152
	v_and_b32_e32 v223, 0xffff0000, v152
	v_lshlrev_b32_e32 v224, 16, v153
	v_and_b32_e32 v225, 0xffff0000, v153
	v_pk_fma_f32 v[58:59], s[24:25], v[58:59], v[222:223]
	v_pk_fma_f32 v[60:61], s[24:25], v[60:61], v[224:225]
	v_cvt_pk_bf16_f32 v150, v62, v63
	v_mul_f32_e32 v226, v63, v63
	v_mul_f32_e32 v222, v65, v65
	v_cvt_pk_bf16_f32 v151, v64, v65
	v_fmac_f32_e32 v226, v62, v62
	v_fmac_f32_e32 v222, v64, v64
	v_cvt_pk_bf16_f32 v152, v58, v59
	v_add_f32_e32 v226, v226, v222
	v_mul_f32_e32 v222, v59, v59
	v_cvt_pk_bf16_f32 v153, v60, v61
	v_fmac_f32_e32 v222, v58, v58
	v_mul_f32_e32 v223, v61, v61
	v_add_f32_e32 v226, v222, v226
	v_fmac_f32_e32 v223, v60, v60
	v_add_f32_e32 v226, v223, v226
	v_lshlrev_b32_e32 v222, 16, v146
	v_and_b32_e32 v223, 0xffff0000, v146
	v_lshlrev_b32_e32 v224, 16, v147
	v_and_b32_e32 v225, 0xffff0000, v147
	v_pk_fma_f32 v[54:55], s[24:25], v[54:55], v[222:223]
	v_pk_fma_f32 v[56:57], s[24:25], v[56:57], v[224:225]
	v_lshlrev_b32_e32 v222, 16, v148
	v_and_b32_e32 v223, 0xffff0000, v148
	v_lshlrev_b32_e32 v224, 16, v149
	v_and_b32_e32 v225, 0xffff0000, v149
	v_pk_fma_f32 v[50:51], s[24:25], v[50:51], v[222:223]
	v_pk_fma_f32 v[52:53], s[24:25], v[52:53], v[224:225]
	v_cvt_pk_bf16_f32 v146, v54, v55
	v_mul_f32_e32 v227, v55, v55
	v_mul_f32_e32 v222, v57, v57
	v_cvt_pk_bf16_f32 v147, v56, v57
	v_fmac_f32_e32 v227, v54, v54
	v_fmac_f32_e32 v222, v56, v56
	v_cvt_pk_bf16_f32 v148, v50, v51
	v_add_f32_e32 v227, v227, v222
	v_mul_f32_e32 v222, v51, v51
	v_cvt_pk_bf16_f32 v149, v52, v53
	v_fmac_f32_e32 v222, v50, v50
	v_mul_f32_e32 v223, v53, v53
	v_add_f32_e32 v227, v222, v227
	v_fmac_f32_e32 v223, v52, v52
	v_add_f32_e32 v227, v223, v227
	ds_bpermute_b32 v150, v229, v150
	ds_bpermute_b32 v151, v229, v151
	ds_bpermute_b32 v152, v229, v152
	ds_bpermute_b32 v153, v229, v153
	ds_bpermute_b32 v146, v229, v146
	ds_bpermute_b32 v147, v229, v147
	ds_bpermute_b32 v148, v229, v148
	ds_bpermute_b32 v149, v229, v149
	v_add_f32_e32 v54, v226, v227
	s_waitcnt vmcnt(10)
	ds_bpermute_b32 v126, v228, v126
	ds_bpermute_b32 v127, v228, v127
	ds_bpermute_b32 v128, v228, v128
	ds_bpermute_b32 v129, v228, v129
	ds_bpermute_b32 v122, v228, v122
	ds_bpermute_b32 v123, v228, v123
	ds_bpermute_b32 v124, v228, v124
	ds_bpermute_b32 v125, v228, v125
	s_waitcnt lgkmcnt(8)
;     __device__ __forceinline__ void operator()(const f32x4 (&acc)[2][2][4][2], const Unit& u, const LAS float* rsl, int wr, int wc, int fr, int fq) const {
;     ...
;                 for (int bj = 0; bj < 2; ++bj) xin[ai][m][bj] = *(const bf16x8*)(base + (size_t)(ai * HALF + m * 16) * D + bj * HALF);
; #pragma unroll
;         for (int ai = 0; ai < 2; ++ai)
; #pragma unroll
;             for (int m = 0; m < 4; ++m) {
;                 const int row = u.pm * BM + ai * HALF + wr * 64 + m * 16 + fr;
;                 float ss = 0.f;
; #pragma unroll
;                 for (int bj = 0; bj < 2; ++bj) {
;                     float xf[8]; unpack8(xin[ai][m][bj], xf);
;                     f32x4 x0 = (f32x4){xf[0], xf[1], xf[2], xf[3]}, x1 = (f32x4){xf[4], xf[5], xf[6], xf[7]};
;                     x0 += acc[ai][bj][m][0] * s; x1 += acc[ai][bj][m][1] * s;
;                     *(bf16x8*)(base + (size_t)(ai * HALF + m * 16) * D + bj * HALF) = pack8v(x0, x1);
;                     ss += (x0[0] * x0[0] + x0[1] * x0[1]) + (x0[2] * x0[2] + x0[3] * x0[3]) + (x1[0] * x1[0] + x1[1] * x1[1]) + (x1[2] * x1[2] + x1[3] * x1[3]);
	v_add_co_u32_e32 v220, vcc, s91, v206
	s_nop 1
	v_addc_co_u32_e32 v221, vcc, 0, v207, vcc
	global_store_dwordx4 v[220:221], v[150:153], off
	global_store_dwordx4 v[220:221], v[146:149], off offset:256
	v_lshlrev_b32_e32 v222, 16, v142
	v_and_b32_e32 v223, 0xffff0000, v142
	v_lshlrev_b32_e32 v224, 16, v143
	v_and_b32_e32 v225, 0xffff0000, v143
	v_pk_fma_f32 v[46:47], s[24:25], v[46:47], v[222:223]
	v_pk_fma_f32 v[48:49], s[24:25], v[48:49], v[224:225]
	v_lshlrev_b32_e32 v222, 16, v144
	v_and_b32_e32 v223, 0xffff0000, v144
	v_lshlrev_b32_e32 v224, 16, v145
	v_and_b32_e32 v225, 0xffff0000, v145
	v_pk_fma_f32 v[42:43], s[24:25], v[42:43], v[222:223]
	v_pk_fma_f32 v[44:45], s[24:25], v[44:45], v[224:225]
	v_cvt_pk_bf16_f32 v142, v46, v47
	v_mul_f32_e32 v226, v47, v47
	v_mul_f32_e32 v222, v49, v49
	v_cvt_pk_bf16_f32 v143, v48, v49
	v_fmac_f32_e32 v226, v46, v46
	v_fmac_f32_e32 v222, v48, v48
	v_cvt_pk_bf16_f32 v144, v42, v43
	v_add_f32_e32 v226, v226, v222
	v_mul_f32_e32 v222, v43, v43
	v_cvt_pk_bf16_f32 v145, v44, v45
	v_fmac_f32_e32 v222, v42, v42
	v_mul_f32_e32 v223, v45, v45
	v_add_f32_e32 v226, v222, v226
	v_fmac_f32_e32 v223, v44, v44
	v_add_f32_e32 v226, v223, v226
	v_lshlrev_b32_e32 v222, 16, v138
	v_and_b32_e32 v223, 0xffff0000, v138
	v_lshlrev_b32_e32 v224, 16, v139
	v_and_b32_e32 v225, 0xffff0000, v139
	v_pk_fma_f32 v[38:39], s[24:25], v[38:39], v[222:223]
	v_pk_fma_f32 v[40:41], s[24:25], v[40:41], v[224:225]
	v_lshlrev_b32_e32 v222, 16, v140
	v_and_b32_e32 v223, 0xffff0000, v140
	v_lshlrev_b32_e32 v224, 16, v141
	v_and_b32_e32 v225, 0xffff0000, v141
	v_pk_fma_f32 v[34:35], s[24:25], v[34:35], v[222:223]
	v_pk_fma_f32 v[36:37], s[24:25], v[36:37], v[224:225]
	v_cvt_pk_bf16_f32 v138, v38, v39
	v_mul_f32_e32 v227, v39, v39
	v_mul_f32_e32 v222, v41, v41
	v_cvt_pk_bf16_f32 v139, v40, v41
	v_fmac_f32_e32 v227, v38, v38
	v_fmac_f32_e32 v222, v40, v40
	v_cvt_pk_bf16_f32 v140, v34, v35
	v_add_f32_e32 v227, v227, v222
	v_mul_f32_e32 v222, v35, v35
	v_cvt_pk_bf16_f32 v141, v36, v37
	v_fmac_f32_e32 v222, v34, v34
	v_mul_f32_e32 v223, v37, v37
	v_add_f32_e32 v227, v222, v227
	v_fmac_f32_e32 v223, v36, v36
	v_add_f32_e32 v227, v223, v227
	ds_bpermute_b32 v142, v229, v142
	ds_bpermute_b32 v143, v229, v143
	ds_bpermute_b32 v144, v229, v144
	ds_bpermute_b32 v145, v229, v145
	ds_bpermute_b32 v138, v229, v138
	ds_bpermute_b32 v139, v229, v139
	ds_bpermute_b32 v140, v229, v140
	ds_bpermute_b32 v141, v229, v141
	v_add_f32_e32 v38, v226, v227
	s_waitcnt vmcnt(10)
	ds_bpermute_b32 v110, v228, v110
	ds_bpermute_b32 v111, v228, v111
	ds_bpermute_b32 v112, v228, v112
	ds_bpermute_b32 v113, v228, v113
	ds_bpermute_b32 v106, v228, v106
	ds_bpermute_b32 v107, v228, v107
	ds_bpermute_b32 v108, v228, v108
	ds_bpermute_b32 v109, v228, v109
	s_waitcnt lgkmcnt(8)
	v_add_co_u32_e32 v220, vcc, s84, v206
	s_nop 1
	v_addc_co_u32_e32 v221, vcc, 0, v207, vcc
	global_store_dwordx4 v[220:221], v[142:145], off
	global_store_dwordx4 v[220:221], v[138:141], off offset:256
	v_lshlrev_b32_e32 v222, 16, v126
	v_and_b32_e32 v223, 0xffff0000, v126
	v_lshlrev_b32_e32 v224, 16, v127
	v_and_b32_e32 v225, 0xffff0000, v127
	v_pk_fma_f32 v[30:31], s[24:25], v[30:31], v[222:223]
	v_pk_fma_f32 v[32:33], s[24:25], v[32:33], v[224:225]
	v_lshlrev_b32_e32 v222, 16, v128
	v_and_b32_e32 v223, 0xffff0000, v128
	v_lshlrev_b32_e32 v224, 16, v129
	v_and_b32_e32 v225, 0xffff0000, v129
	v_pk_fma_f32 v[26:27], s[24:25], v[26:27], v[222:223]
	v_pk_fma_f32 v[28:29], s[24:25], v[28:29], v[224:225]
	v_cvt_pk_bf16_f32 v126, v30, v31
	v_mul_f32_e32 v226, v31, v31
	v_mul_f32_e32 v222, v33, v33
	v_cvt_pk_bf16_f32 v127, v32, v33
	v_fmac_f32_e32 v226, v30, v30
	v_fmac_f32_e32 v222, v32, v32
	v_cvt_pk_bf16_f32 v128, v26, v27
	v_add_f32_e32 v226, v226, v222
	v_mul_f32_e32 v222, v27, v27
	v_cvt_pk_bf16_f32 v129, v28, v29
	v_fmac_f32_e32 v222, v26, v26
	v_mul_f32_e32 v223, v29, v29
	v_add_f32_e32 v226, v222, v226
	v_fmac_f32_e32 v223, v28, v28
	v_add_f32_e32 v226, v223, v226
	v_lshlrev_b32_e32 v222, 16, v122
	v_and_b32_e32 v223, 0xffff0000, v122
	v_lshlrev_b32_e32 v224, 16, v123
	v_and_b32_e32 v225, 0xffff0000, v123
	v_pk_fma_f32 v[22:23], s[24:25], v[22:23], v[222:223]
	v_pk_fma_f32 v[24:25], s[24:25], v[24:25], v[224:225]
	v_lshlrev_b32_e32 v222, 16, v124
	v_and_b32_e32 v223, 0xffff0000, v124
	v_lshlrev_b32_e32 v224, 16, v125
	v_and_b32_e32 v225, 0xffff0000, v125
	v_pk_fma_f32 v[18:19], s[24:25], v[18:19], v[222:223]
	v_pk_fma_f32 v[20:21], s[24:25], v[20:21], v[224:225]
	v_cvt_pk_bf16_f32 v122, v22, v23
	v_mul_f32_e32 v227, v23, v23
	v_mul_f32_e32 v222, v25, v25
	v_cvt_pk_bf16_f32 v123, v24, v25
	v_fmac_f32_e32 v227, v22, v22
	v_fmac_f32_e32 v222, v24, v24
	v_cvt_pk_bf16_f32 v124, v18, v19
	v_add_f32_e32 v227, v227, v222
	v_mul_f32_e32 v222, v19, v19
	v_cvt_pk_bf16_f32 v125, v20, v21
	v_fmac_f32_e32 v222, v18, v18
	v_mul_f32_e32 v223, v21, v21
	v_add_f32_e32 v227, v222, v227
	v_fmac_f32_e32 v223, v20, v20
	v_add_f32_e32 v227, v223, v227
	ds_bpermute_b32 v126, v229, v126
	ds_bpermute_b32 v127, v229, v127
	ds_bpermute_b32 v128, v229, v128
	ds_bpermute_b32 v129, v229, v129
	ds_bpermute_b32 v122, v229, v122
	ds_bpermute_b32 v123, v229, v123
	ds_bpermute_b32 v124, v229, v124
	ds_bpermute_b32 v125, v229, v125
	v_add_f32_e32 v22, v226, v227
	s_waitcnt lgkmcnt(0)
;     __device__ __forceinline__ void operator()(const f32x4 (&acc)[2][2][4][2], const Unit& u, const LAS float* rsl, int wr, int wc, int fr, int fq) const {
;     ...
;                 for (int bj = 0; bj < 2; ++bj) xin[ai][m][bj] = *(const bf16x8*)(base + (size_t)(ai * HALF + m * 16) * D + bj * HALF);
; #pragma unroll
;         for (int ai = 0; ai < 2; ++ai)
; #pragma unroll
;             for (int m = 0; m < 4; ++m) {
;                 const int row = u.pm * BM + ai * HALF + wr * 64 + m * 16 + fr;
;                 float ss = 0.f;
; #pragma unroll
;                 for (int bj = 0; bj < 2; ++bj) {
;                     float xf[8]; unpack8(xin[ai][m][bj], xf);
;                     f32x4 x0 = (f32x4){xf[0], xf[1], xf[2], xf[3]}, x1 = (f32x4){xf[4], xf[5], xf[6], xf[7]};
;                     x0 += acc[ai][bj][m][0] * s; x1 += acc[ai][bj][m][1] * s;
;                     *(bf16x8*)(base + (size_t)(ai * HALF + m * 16) * D + bj * HALF) = pack8v(x0, x1);
;                     ss += (x0[0] * x0[0] + x0[1] * x0[1]) + (x0[2] * x0[2] + x0[3] * x0[3]) + (x1[0] * x1[0] + x1[1] * x1[1]) + (x1[2] * x1[2] + x1[3] * x1[3]);
;                 }
;                 ss += __shfl_xor(ss, 16); ss += __shfl_xor(ss, 32);
;                 if (fq == 0) SS[(size_t)row * 16 + u.pn * 4 + wc] = ss;
	v_add_co_u32_e32 v220, vcc, s85, v206
	s_nop 1
	v_addc_co_u32_e32 v221, vcc, 0, v207, vcc
	global_store_dwordx4 v[220:221], v[126:129], off
	global_store_dwordx4 v[220:221], v[122:125], off offset:256
	v_lshlrev_b32_e32 v222, 16, v110
	v_and_b32_e32 v223, 0xffff0000, v110
	v_lshlrev_b32_e32 v224, 16, v111
	v_and_b32_e32 v225, 0xffff0000, v111
	v_pk_fma_f32 v[14:15], s[24:25], v[14:15], v[222:223]
	v_pk_fma_f32 v[16:17], s[24:25], v[16:17], v[224:225]
	v_lshlrev_b32_e32 v222, 16, v112
	v_and_b32_e32 v223, 0xffff0000, v112
	v_lshlrev_b32_e32 v224, 16, v113
	v_and_b32_e32 v225, 0xffff0000, v113
	v_pk_fma_f32 v[10:11], s[24:25], v[10:11], v[222:223]
	v_pk_fma_f32 v[12:13], s[24:25], v[12:13], v[224:225]
	v_cvt_pk_bf16_f32 v110, v14, v15
	v_mul_f32_e32 v226, v15, v15
	v_mul_f32_e32 v222, v17, v17
	v_cvt_pk_bf16_f32 v111, v16, v17
	v_fmac_f32_e32 v226, v14, v14
	v_fmac_f32_e32 v222, v16, v16
	v_cvt_pk_bf16_f32 v112, v10, v11
	v_add_f32_e32 v226, v226, v222
	v_mul_f32_e32 v222, v11, v11
	v_cvt_pk_bf16_f32 v113, v12, v13
	v_fmac_f32_e32 v222, v10, v10
	v_mul_f32_e32 v223, v13, v13
	v_add_f32_e32 v226, v222, v226
	v_fmac_f32_e32 v223, v12, v12
	v_add_f32_e32 v226, v223, v226
	v_lshlrev_b32_e32 v222, 16, v106
	v_and_b32_e32 v223, 0xffff0000, v106
	v_lshlrev_b32_e32 v224, 16, v107
	v_and_b32_e32 v225, 0xffff0000, v107
	v_pk_fma_f32 v[6:7], s[24:25], v[6:7], v[222:223]
	v_pk_fma_f32 v[8:9], s[24:25], v[8:9], v[224:225]
	v_lshlrev_b32_e32 v222, 16, v108
	v_and_b32_e32 v223, 0xffff0000, v108
	v_lshlrev_b32_e32 v224, 16, v109
	v_and_b32_e32 v225, 0xffff0000, v109
	v_pk_fma_f32 v[2:3], s[24:25], v[2:3], v[222:223]
	v_pk_fma_f32 v[4:5], s[24:25], v[4:5], v[224:225]
	v_cvt_pk_bf16_f32 v106, v6, v7
	v_mul_f32_e32 v227, v7, v7
	v_mul_f32_e32 v222, v9, v9
	v_cvt_pk_bf16_f32 v107, v8, v9
	v_fmac_f32_e32 v227, v6, v6
	v_fmac_f32_e32 v222, v8, v8
	v_cvt_pk_bf16_f32 v108, v2, v3
	v_add_f32_e32 v227, v227, v222
	v_mul_f32_e32 v222, v3, v3
	v_cvt_pk_bf16_f32 v109, v4, v5
	v_fmac_f32_e32 v222, v2, v2
	v_mul_f32_e32 v223, v5, v5
	v_add_f32_e32 v227, v222, v227
	v_fmac_f32_e32 v223, v4, v4
	v_add_f32_e32 v227, v223, v227
	ds_bpermute_b32 v110, v229, v110
	ds_bpermute_b32 v111, v229, v111
	ds_bpermute_b32 v112, v229, v112
	ds_bpermute_b32 v113, v229, v113
	ds_bpermute_b32 v106, v229, v106
	ds_bpermute_b32 v107, v229, v107
	ds_bpermute_b32 v108, v229, v108
	ds_bpermute_b32 v109, v229, v109
	v_add_f32_e32 v6, v226, v227
	s_waitcnt lgkmcnt(0)
	v_add_co_u32_e32 v220, vcc, s90, v206
	s_nop 1
	v_addc_co_u32_e32 v221, vcc, 0, v207, vcc
	global_store_dwordx4 v[220:221], v[110:113], off
	global_store_dwordx4 v[220:221], v[106:109], off offset:256
	v_xor_b32_e32 v159, 16, v210
	v_lshlrev_b32_e32 v159, 2, v159
	v_xor_b32_e32 v160, 32, v210
	v_lshlrev_b32_e32 v160, 2, v160
	ds_bpermute_b32 v158, v159, v134
	ds_bpermute_b32 v118, v159, v102
	ds_bpermute_b32 v94, v159, v86
	ds_bpermute_b32 v78, v159, v70
	ds_bpermute_b32 v62, v159, v54
	ds_bpermute_b32 v46, v159, v38
	ds_bpermute_b32 v30, v159, v22
	ds_bpermute_b32 v14, v159, v6
	s_waitcnt lgkmcnt(0)
	v_add_f32_e32 v134, v134, v158
	v_add_f32_e32 v102, v102, v118
	v_add_f32_e32 v86, v86, v94
	v_add_f32_e32 v70, v70, v78
	v_add_f32_e32 v54, v54, v62
	v_add_f32_e32 v38, v38, v46
	v_add_f32_e32 v22, v22, v30
	v_add_f32_e32 v6, v6, v14
	ds_bpermute_b32 v158, v160, v134
	ds_bpermute_b32 v118, v160, v102
	ds_bpermute_b32 v94, v160, v86
	ds_bpermute_b32 v78, v160, v70
	ds_bpermute_b32 v62, v160, v54
	ds_bpermute_b32 v46, v160, v38
	ds_bpermute_b32 v30, v160, v22
	ds_bpermute_b32 v14, v160, v6
	v_lshlrev_b64 v[220:221], 6, v[204:205]
	s_lshl_b32 s42, s58, 4
	s_lshl_b32 s43, s52, 2
	s_add_u32 s42, s42, s43
	s_mov_b32 s43, 0
	v_lshl_add_u64 v[220:221], s[10:11], 0, v[220:221]
	v_lshl_add_u64 v[220:221], v[220:221], 0, s[42:43]
	v_add_co_u32_e32 v222, vcc, 0x2000, v220
	v_and_b32_e32 v130, 64, v210
	v_addc_co_u32_e32 v223, vcc, 0, v221, vcc
	v_add_u32_e32 v130, 64, v130
	s_waitcnt lgkmcnt(0)
	v_add_f32_e32 v134, v134, v158
	v_add_f32_e32 v102, v102, v118
	v_add_f32_e32 v86, v86, v94
	v_add_f32_e32 v70, v70, v78
	v_add_f32_e32 v54, v54, v62
	v_add_f32_e32 v38, v38, v46
	v_add_f32_e32 v22, v22, v30
	v_add_f32_e32 v6, v6, v14
	s_and_saveexec_b64 s[44:45], s[0:1]
	global_store_dword v[220:221], v134, off
	global_store_dword v[220:221], v102, off offset:1024
	global_store_dword v[220:221], v86, off offset:2048
	global_store_dword v[220:221], v70, off offset:3072
	global_store_dword v[222:223], v54, off
	global_store_dword v[222:223], v38, off offset:1024
	global_store_dword v[222:223], v22, off offset:2048
	global_store_dword v[222:223], v6, off offset:3072

; __device__ __forceinline__ void band_attn_p2(const Params& P, int l, int b, int c, int h, LAS unsigned char* wl, int lane_) {
;     ...
;     if (c >= 120) {
;         const size_t ob = (size_t)((l * 2 + b) * 512 + (c - 120) * 64);
;         for (int i = 0; i < 8; ++i) { const int row = vr0 + 8 * i; float f[8];
;             unpack8(*(const bf16x8*)(Z + (size_t)(qrow0 + row) * DIN + 512 + h * 64 + 8 * vch), f); store8f(P.out + OFF_KP + ((ob + row) * 8 + h) * 64 + 8 * vch, f);
;             unpack8(*(const bf16x8*)(Z + (size_t)(qrow0 + row) * DIN + 1024 + h * 64 + 8 * vch), f); store8f(P.out + OFF_VP + ((ob + row) * 8 + h) * 64 + 8 * vch, f); }
;     }
.LBB0_711:
	s_cmpk_gt_u32 s8, 0x77
	s_cbranch_scc0 .LBB0_714
	s_lshl_b32 s0, s52, 9
	v_readlane_b32 s1, v255, 15
	s_add_i32 s0, s1, s0
	s_add_i32 s0, s0, s4
	v_ashrrev_i32_e32 v193, 31, v192
	s_ashr_i32 s1, s0, 31
	v_lshl_add_u64 v[68:69], v[192:193], 0, s[0:1]
	v_lshlrev_b64 v[68:69], 11, v[68:69]
	v_readlane_b32 s0, v255, 5
	v_lshlrev_b32_e32 v0, 1, v196
	v_lshl_or_b32 v68, v200, 5, v68
	v_readlane_b32 s1, v255, 6
	s_add_i32 s4, s4, s5
	v_lshl_add_u64 v[66:67], s[40:41], 0, v[0:1]
	v_lshl_add_u64 v[68:69], s[0:1], 0, v[68:69]
	v_add_u32_e32 v0, s4, v192
	s_mov_b64 s[0:1], 0
	v_mad_i64_i32 v[78:79], s[2:3], v0, s66, v[66:67]
	global_load_dwordx4 v[84:87], v[78:79], off offset:1024
	global_load_dwordx4 v[88:91], v[78:79], off offset:2048
	v_add_u32_e32 v82, 8, v0
	v_mad_i64_i32 v[78:79], s[2:3], v82, s66, v[66:67]
	global_load_dwordx4 v[92:95], v[78:79], off offset:1024
	global_load_dwordx4 v[96:99], v[78:79], off offset:2048
	v_add_u32_e32 v82, 16, v0
	v_mad_i64_i32 v[78:79], s[2:3], v82, s66, v[66:67]
	global_load_dwordx4 v[100:103], v[78:79], off offset:1024
	global_load_dwordx4 v[104:107], v[78:79], off offset:2048
	v_add_u32_e32 v82, 24, v0
	v_mad_i64_i32 v[78:79], s[2:3], v82, s66, v[66:67]
	global_load_dwordx4 v[108:111], v[78:79], off offset:1024
	global_load_dwordx4 v[112:115], v[78:79], off offset:2048
	v_add_u32_e32 v82, 32, v0
	v_mad_i64_i32 v[78:79], s[2:3], v82, s66, v[66:67]
	global_load_dwordx4 v[116:119], v[78:79], off offset:1024
	global_load_dwordx4 v[156:159], v[78:79], off offset:2048
	v_add_u32_e32 v82, 40, v0
	v_mad_i64_i32 v[78:79], s[2:3], v82, s66, v[66:67]
	global_load_dwordx4 v[160:163], v[78:79], off offset:1024
	global_load_dwordx4 v[164:167], v[78:79], off offset:2048
	v_add_u32_e32 v82, 48, v0
	v_mad_i64_i32 v[78:79], s[2:3], v82, s66, v[66:67]
	global_load_dwordx4 v[168:171], v[78:79], off offset:1024
	global_load_dwordx4 v[172:175], v[78:79], off offset:2048
	v_add_u32_e32 v82, 56, v0
	v_mad_i64_i32 v[78:79], s[2:3], v82, s66, v[66:67]
	global_load_dwordx4 v[176:179], v[78:79], off offset:1024
	global_load_dwordx4 v[180:183], v[78:79], off offset:2048
	s_nop 1
	s_waitcnt vmcnt(15)
	v_lshlrev_b32_e32 v70, 16, v84
	v_and_b32_e32 v71, 0xffff0000, v84
	v_lshlrev_b32_e32 v72, 16, v85
	v_and_b32_e32 v73, 0xffff0000, v85
	v_lshlrev_b32_e32 v74, 16, v86
	v_and_b32_e32 v75, 0xffff0000, v86
	v_lshlrev_b32_e32 v76, 16, v87
	v_and_b32_e32 v77, 0xffff0000, v87
	s_mov_b32 s2, 0x4200000
	v_add_co_u32_e32 v80, vcc, s2, v68
	s_nop 1
	v_addc_co_u32_e32 v81, vcc, 0, v69, vcc
	global_store_dwordx4 v[80:81], v[70:73], off
	global_store_dwordx4 v[80:81], v[74:77], off offset:16
	s_nop 1
	s_waitcnt vmcnt(16)
	v_lshlrev_b32_e32 v70, 16, v88
	v_and_b32_e32 v71, 0xffff0000, v88
	v_lshlrev_b32_e32 v72, 16, v89
	v_and_b32_e32 v73, 0xffff0000, v89
	v_lshlrev_b32_e32 v74, 16, v90
	v_and_b32_e32 v75, 0xffff0000, v90
	v_lshlrev_b32_e32 v76, 16, v91
	v_and_b32_e32 v77, 0xffff0000, v91
	s_mov_b32 s2, 0x4a00000
	v_add_co_u32_e32 v80, vcc, s2, v68
	s_nop 1
	v_addc_co_u32_e32 v81, vcc, 0, v69, vcc
	global_store_dwordx4 v[80:81], v[70:73], off
	global_store_dwordx4 v[80:81], v[74:77], off offset:16
	s_nop 1
	s_waitcnt vmcnt(17)
	v_lshlrev_b32_e32 v70, 16, v92
	v_and_b32_e32 v71, 0xffff0000, v92
	v_lshlrev_b32_e32 v72, 16, v93
	v_and_b32_e32 v73, 0xffff0000, v93
	v_lshlrev_b32_e32 v74, 16, v94
	v_and_b32_e32 v75, 0xffff0000, v94
	v_lshlrev_b32_e32 v76, 16, v95
	v_and_b32_e32 v77, 0xffff0000, v95
	s_mov_b32 s2, 0x4204000
	v_add_co_u32_e32 v80, vcc, s2, v68
	s_nop 1
	v_addc_co_u32_e32 v81, vcc, 0, v69, vcc
	global_store_dwordx4 v[80:81], v[70:73], off
	global_store_dwordx4 v[80:81], v[74:77], off offset:16
	s_nop 1
	s_waitcnt vmcnt(18)
	v_lshlrev_b32_e32 v70, 16, v96
	v_and_b32_e32 v71, 0xffff0000, v96
	v_lshlrev_b32_e32 v72, 16, v97
	v_and_b32_e32 v73, 0xffff0000, v97
	v_lshlrev_b32_e32 v74, 16, v98
	v_and_b32_e32 v75, 0xffff0000, v98
	v_lshlrev_b32_e32 v76, 16, v99
	v_and_b32_e32 v77, 0xffff0000, v99
	s_mov_b32 s2, 0x4a04000
	v_add_co_u32_e32 v80, vcc, s2, v68
	s_nop 1
	v_addc_co_u32_e32 v81, vcc, 0, v69, vcc
	global_store_dwordx4 v[80:81], v[70:73], off
	global_store_dwordx4 v[80:81], v[74:77], off offset:16
	s_nop 1
	s_waitcnt vmcnt(19)
	v_lshlrev_b32_e32 v70, 16, v100
	v_and_b32_e32 v71, 0xffff0000, v100
	v_lshlrev_b32_e32 v72, 16, v101
	v_and_b32_e32 v73, 0xffff0000, v101
	v_lshlrev_b32_e32 v74, 16, v102
	v_and_b32_e32 v75, 0xffff0000, v102
	v_lshlrev_b32_e32 v76, 16, v103
	v_and_b32_e32 v77, 0xffff0000, v103
	s_mov_b32 s2, 0x4208000
	v_add_co_u32_e32 v80, vcc, s2, v68
	s_nop 1
	v_addc_co_u32_e32 v81, vcc, 0, v69, vcc
	global_store_dwordx4 v[80:81], v[70:73], off
	global_store_dwordx4 v[80:81], v[74:77], off offset:16
	s_nop 1
	s_waitcnt vmcnt(20)
	v_lshlrev_b32_e32 v70, 16, v104
	v_and_b32_e32 v71, 0xffff0000, v104
	v_lshlrev_b32_e32 v72, 16, v105
	v_and_b32_e32 v73, 0xffff0000, v105
	v_lshlrev_b32_e32 v74, 16, v106
	v_and_b32_e32 v75, 0xffff0000, v106
	v_lshlrev_b32_e32 v76, 16, v107
	v_and_b32_e32 v77, 0xffff0000, v107
	s_mov_b32 s2, 0x4a08000
	v_add_co_u32_e32 v80, vcc, s2, v68
	s_nop 1
	v_addc_co_u32_e32 v81, vcc, 0, v69, vcc
	global_store_dwordx4 v[80:81], v[70:73], off
	global_store_dwordx4 v[80:81], v[74:77], off offset:16
	s_nop 1
	s_waitcnt vmcnt(21)
; __device__ __forceinline__ void band_attn_p2(const Params& P, int l, int b, int c, int h, LAS unsigned char* wl, int lane_) {
;     ...
;     if (c >= 120) {
;         const size_t ob = (size_t)((l * 2 + b) * 512 + (c - 120) * 64);
;         for (int i = 0; i < 8; ++i) { const int row = vr0 + 8 * i; float f[8];
;             unpack8(*(const bf16x8*)(Z + (size_t)(qrow0 + row) * DIN + 512 + h * 64 + 8 * vch), f); store8f(P.out + OFF_KP + ((ob + row) * 8 + h) * 64 + 8 * vch, f);
;             unpack8(*(const bf16x8*)(Z + (size_t)(qrow0 + row) * DIN + 1024 + h * 64 + 8 * vch), f); store8f(P.out + OFF_VP + ((ob + row) * 8 + h) * 64 + 8 * vch, f); }
;     }
	v_lshlrev_b32_e32 v70, 16, v108
	v_and_b32_e32 v71, 0xffff0000, v108
	v_lshlrev_b32_e32 v72, 16, v109
	v_and_b32_e32 v73, 0xffff0000, v109
	v_lshlrev_b32_e32 v74, 16, v110
	v_and_b32_e32 v75, 0xffff0000, v110
	v_lshlrev_b32_e32 v76, 16, v111
	v_and_b32_e32 v77, 0xffff0000, v111
	s_mov_b32 s2, 0x420c000
	v_add_co_u32_e32 v80, vcc, s2, v68
	s_nop 1
	v_addc_co_u32_e32 v81, vcc, 0, v69, vcc
	global_store_dwordx4 v[80:81], v[70:73], off
	global_store_dwordx4 v[80:81], v[74:77], off offset:16
	s_nop 1
	s_waitcnt vmcnt(22)
	v_lshlrev_b32_e32 v70, 16, v112
	v_and_b32_e32 v71, 0xffff0000, v112
	v_lshlrev_b32_e32 v72, 16, v113
	v_and_b32_e32 v73, 0xffff0000, v113
	v_lshlrev_b32_e32 v74, 16, v114
	v_and_b32_e32 v75, 0xffff0000, v114
	v_lshlrev_b32_e32 v76, 16, v115
	v_and_b32_e32 v77, 0xffff0000, v115
	s_mov_b32 s2, 0x4a0c000
	v_add_co_u32_e32 v80, vcc, s2, v68
	s_nop 1
	v_addc_co_u32_e32 v81, vcc, 0, v69, vcc
	global_store_dwordx4 v[80:81], v[70:73], off
	global_store_dwordx4 v[80:81], v[74:77], off offset:16
	s_nop 1
	s_waitcnt vmcnt(23)
	v_lshlrev_b32_e32 v70, 16, v116
	v_and_b32_e32 v71, 0xffff0000, v116
	v_lshlrev_b32_e32 v72, 16, v117
	v_and_b32_e32 v73, 0xffff0000, v117
	v_lshlrev_b32_e32 v74, 16, v118
	v_and_b32_e32 v75, 0xffff0000, v118
	v_lshlrev_b32_e32 v76, 16, v119
	v_and_b32_e32 v77, 0xffff0000, v119
	s_mov_b32 s2, 0x4210000
	v_add_co_u32_e32 v80, vcc, s2, v68
	s_nop 1
	v_addc_co_u32_e32 v81, vcc, 0, v69, vcc
	global_store_dwordx4 v[80:81], v[70:73], off
	global_store_dwordx4 v[80:81], v[74:77], off offset:16
	s_nop 1
	s_waitcnt vmcnt(24)
	v_lshlrev_b32_e32 v70, 16, v156
	v_and_b32_e32 v71, 0xffff0000, v156
	v_lshlrev_b32_e32 v72, 16, v157
	v_and_b32_e32 v73, 0xffff0000, v157
	v_lshlrev_b32_e32 v74, 16, v158
	v_and_b32_e32 v75, 0xffff0000, v158
	v_lshlrev_b32_e32 v76, 16, v159
	v_and_b32_e32 v77, 0xffff0000, v159
	s_mov_b32 s2, 0x4a10000
	v_add_co_u32_e32 v80, vcc, s2, v68
	s_nop 1
	v_addc_co_u32_e32 v81, vcc, 0, v69, vcc
	global_store_dwordx4 v[80:81], v[70:73], off
	global_store_dwordx4 v[80:81], v[74:77], off offset:16
	s_nop 1
	s_waitcnt vmcnt(25)
	v_lshlrev_b32_e32 v70, 16, v160
	v_and_b32_e32 v71, 0xffff0000, v160
	v_lshlrev_b32_e32 v72, 16, v161
	v_and_b32_e32 v73, 0xffff0000, v161
	v_lshlrev_b32_e32 v74, 16, v162
	v_and_b32_e32 v75, 0xffff0000, v162
	v_lshlrev_b32_e32 v76, 16, v163
	v_and_b32_e32 v77, 0xffff0000, v163
	s_mov_b32 s2, 0x4214000
	v_add_co_u32_e32 v80, vcc, s2, v68
	s_nop 1
	v_addc_co_u32_e32 v81, vcc, 0, v69, vcc
	global_store_dwordx4 v[80:81], v[70:73], off
	global_store_dwordx4 v[80:81], v[74:77], off offset:16
	s_nop 1
	s_waitcnt vmcnt(26)
	v_lshlrev_b32_e32 v70, 16, v164
	v_and_b32_e32 v71, 0xffff0000, v164
	v_lshlrev_b32_e32 v72, 16, v165
	v_and_b32_e32 v73, 0xffff0000, v165
	v_lshlrev_b32_e32 v74, 16, v166
	v_and_b32_e32 v75, 0xffff0000, v166
	v_lshlrev_b32_e32 v76, 16, v167
	v_and_b32_e32 v77, 0xffff0000, v167
	s_mov_b32 s2, 0x4a14000
	v_add_co_u32_e32 v80, vcc, s2, v68
	s_nop 1
	v_addc_co_u32_e32 v81, vcc, 0, v69, vcc
	global_store_dwordx4 v[80:81], v[70:73], off
	global_store_dwordx4 v[80:81], v[74:77], off offset:16
	s_nop 1
	s_waitcnt vmcnt(27)
	v_lshlrev_b32_e32 v70, 16, v168
	v_and_b32_e32 v71, 0xffff0000, v168
	v_lshlrev_b32_e32 v72, 16, v169
	v_and_b32_e32 v73, 0xffff0000, v169
	v_lshlrev_b32_e32 v74, 16, v170
	v_and_b32_e32 v75, 0xffff0000, v170
	v_lshlrev_b32_e32 v76, 16, v171
	v_and_b32_e32 v77, 0xffff0000, v171
	s_mov_b32 s2, 0x4218000
	v_add_co_u32_e32 v80, vcc, s2, v68
	s_nop 1
	v_addc_co_u32_e32 v81, vcc, 0, v69, vcc
	global_store_dwordx4 v[80:81], v[70:73], off
	global_store_dwordx4 v[80:81], v[74:77], off offset:16
	s_nop 1
	s_waitcnt vmcnt(28)
	v_lshlrev_b32_e32 v70, 16, v172
	v_and_b32_e32 v71, 0xffff0000, v172
	v_lshlrev_b32_e32 v72, 16, v173
	v_and_b32_e32 v73, 0xffff0000, v173
	v_lshlrev_b32_e32 v74, 16, v174
	v_and_b32_e32 v75, 0xffff0000, v174
	v_lshlrev_b32_e32 v76, 16, v175
	v_and_b32_e32 v77, 0xffff0000, v175
	s_mov_b32 s2, 0x4a18000
	v_add_co_u32_e32 v80, vcc, s2, v68
	s_nop 1
	v_addc_co_u32_e32 v81, vcc, 0, v69, vcc
	global_store_dwordx4 v[80:81], v[70:73], off
	global_store_dwordx4 v[80:81], v[74:77], off offset:16
	s_nop 1
	s_waitcnt vmcnt(29)
	v_lshlrev_b32_e32 v70, 16, v176
	v_and_b32_e32 v71, 0xffff0000, v176
	v_lshlrev_b32_e32 v72, 16, v177
	v_and_b32_e32 v73, 0xffff0000, v177
	v_lshlrev_b32_e32 v74, 16, v178
	v_and_b32_e32 v75, 0xffff0000, v178
	v_lshlrev_b32_e32 v76, 16, v179
	v_and_b32_e32 v77, 0xffff0000, v179
	s_mov_b32 s2, 0x421c000
	v_add_co_u32_e32 v80, vcc, s2, v68
	s_nop 1
	v_addc_co_u32_e32 v81, vcc, 0, v69, vcc
	global_store_dwordx4 v[80:81], v[70:73], off
	global_store_dwordx4 v[80:81], v[74:77], off offset:16
	s_nop 1
	s_waitcnt vmcnt(30)
	v_lshlrev_b32_e32 v70, 16, v180
	v_and_b32_e32 v71, 0xffff0000, v180
	v_lshlrev_b32_e32 v72, 16, v181
	v_and_b32_e32 v73, 0xffff0000, v181
	v_lshlrev_b32_e32 v74, 16, v182
	v_and_b32_e32 v75, 0xffff0000, v182
	v_lshlrev_b32_e32 v76, 16, v183
	v_and_b32_e32 v77, 0xffff0000, v183
	s_mov_b32 s2, 0x4a1c000
	v_add_co_u32_e32 v80, vcc, s2, v68
	s_nop 1
	v_addc_co_u32_e32 v81, vcc, 0, v69, vcc
	global_store_dwordx4 v[80:81], v[70:73], off
	global_store_dwordx4 v[80:81], v[74:77], off offset:16
